# combination: A-fragment ds_reads first in SP1 segments + later leading-half alignment barrier + trailing-half re-offset barrier in front of the K-loop + scan priority raise
# speedup vs baseline: 1.0015x; 1.0015x over previous
.Lrealign_0:
.LBB0_133:
	s_add_u32 vcc_lo, s0, 0xffffc000
	s_addc_u32 vcc_hi, s1, -1
	s_mov_b32 m0, s52
	s_nop 0
	global_load_lds_dwordx4 v158, vcc
	s_mov_b32 m0, s53
	s_nop 0
	global_load_lds_dwordx4 v160, vcc
	ds_read_b128 v[174:177], v225
	ds_read_b128 v[178:181], v225 offset:1024
	ds_read_b128 v[182:185], v225 offset:2048
	ds_read_b128 v[186:189], v225 offset:3072
	ds_read_b128 v[190:193], v225 offset:4096
	ds_read_b128 v[204:207], v225 offset:5120
	ds_read_b128 v[208:211], v225 offset:6144
	ds_read_b128 v[212:215], v225 offset:7168
	ds_read_b128 v[130:133], v224
	ds_read_b128 v[134:137], v224 offset:1024
	ds_read_b128 v[138:141], v224 offset:2048
	ds_read_b128 v[142:145], v224 offset:3072
	ds_read_b128 v[146:149], v224 offset:16384
	ds_read_b128 v[162:165], v224 offset:17408
	ds_read_b128 v[166:169], v224 offset:18432
	ds_read_b128 v[170:173], v224 offset:19456
	s_add_u32 s4, s0, 0x100
	s_addc_u32 s5, s1, 0
	s_add_i32 s58, 0, 0x10000
	s_cmp_eq_u32 s57, 28
	s_cselect_b32 s35, s27, s5
	s_cselect_b32 s34, s26, s4
	s_cselect_b32 s31, s25, s51
	s_cselect_b32 s30, s37, s50
	s_add_i32 s59, 0, 0x14000
	s_add_i32 m0, s38, 0xc000
	s_nop 0
	global_load_lds_dwordx4 v158, s[0:1]
	s_add_i32 m0, s38, 0xe000
	s_nop 0
	global_load_lds_dwordx4 v160, s[0:1]
	s_waitcnt vmcnt(8)
	s_waitcnt lgkmcnt(0)
	v_mfma_f32_16x16x32_bf16 v[126:129], v[130:133], v[174:177], v[126:129]
	v_mfma_f32_16x16x32_bf16 v[126:129], v[134:137], v[178:181], v[126:129]
	s_barrier
	s_setprio 1
	v_mfma_f32_16x16x32_bf16 v[122:125], v[142:145], v[178:181], v[122:125]
	v_mfma_f32_16x16x32_bf16 v[122:125], v[138:141], v[174:177], v[122:125]
	v_mfma_f32_16x16x32_bf16 v[106:109], v[138:141], v[182:185], v[106:109]
	v_mfma_f32_16x16x32_bf16 v[106:109], v[142:145], v[186:189], v[106:109]
	v_mfma_f32_16x16x32_bf16 v[110:113], v[134:137], v[186:189], v[110:113]
	v_mfma_f32_16x16x32_bf16 v[110:113], v[130:133], v[182:185], v[110:113]
	v_mfma_f32_16x16x32_bf16 v[94:97], v[130:133], v[190:193], v[94:97]
	v_mfma_f32_16x16x32_bf16 v[94:97], v[134:137], v[204:207], v[94:97]
	v_mfma_f32_16x16x32_bf16 v[90:93], v[142:145], v[204:207], v[90:93]
	v_mfma_f32_16x16x32_bf16 v[90:93], v[138:141], v[190:193], v[90:93]
	v_mfma_f32_16x16x32_bf16 v[74:77], v[138:141], v[208:211], v[74:77]
	v_mfma_f32_16x16x32_bf16 v[74:77], v[142:145], v[212:215], v[74:77]
	v_mfma_f32_16x16x32_bf16 v[78:81], v[134:137], v[212:215], v[78:81]
	v_mfma_f32_16x16x32_bf16 v[78:81], v[130:133], v[208:211], v[78:81]
	v_mfma_f32_16x16x32_bf16 v[118:121], v[146:149], v[174:177], v[118:121]
	v_mfma_f32_16x16x32_bf16 v[118:121], v[162:165], v[178:181], v[118:121]
	v_mfma_f32_16x16x32_bf16 v[114:117], v[170:173], v[178:181], v[114:117]
	v_mfma_f32_16x16x32_bf16 v[114:117], v[166:169], v[174:177], v[114:117]
	v_mfma_f32_16x16x32_bf16 v[98:101], v[166:169], v[182:185], v[98:101]
	v_mfma_f32_16x16x32_bf16 v[98:101], v[170:173], v[186:189], v[98:101]
	v_mfma_f32_16x16x32_bf16 v[102:105], v[162:165], v[186:189], v[102:105]
	v_mfma_f32_16x16x32_bf16 v[102:105], v[146:149], v[182:185], v[102:105]
	v_mfma_f32_16x16x32_bf16 v[86:89], v[146:149], v[190:193], v[86:89]
	v_mfma_f32_16x16x32_bf16 v[86:89], v[162:165], v[204:207], v[86:89]
	v_mfma_f32_16x16x32_bf16 v[82:85], v[170:173], v[204:207], v[82:85]
	v_mfma_f32_16x16x32_bf16 v[82:85], v[166:169], v[190:193], v[82:85]
	v_mfma_f32_16x16x32_bf16 v[66:69], v[166:169], v[208:211], v[66:69]
	v_mfma_f32_16x16x32_bf16 v[66:69], v[170:173], v[212:215], v[66:69]
	v_mfma_f32_16x16x32_bf16 v[70:73], v[162:165], v[212:215], v[70:73]
	v_mfma_f32_16x16x32_bf16 v[70:73], v[146:149], v[208:211], v[70:73]
	s_setprio 0
	s_barrier
	ds_read_b128 v[174:177], v225 offset:16384
	ds_read_b128 v[178:181], v225 offset:17408
	ds_read_b128 v[182:185], v225 offset:18432
	ds_read_b128 v[186:189], v225 offset:19456
	ds_read_b128 v[190:193], v225 offset:20480
	ds_read_b128 v[204:207], v225 offset:21504
	ds_read_b128 v[208:211], v225 offset:22528
	ds_read_b128 v[212:215], v225 offset:23552
	s_add_i32 s0, s58, s15
	s_mov_b32 m0, s0
	s_nop 0
	global_load_lds_dwordx4 v152, s[30:31]
	s_add_i32 m0, s0, 0x2000
	s_add_u32 s0, s30, 0x80000
	s_addc_u32 s1, s31, 0
	s_add_i32 s58, s59, s15
	global_load_lds_dwordx4 v156, s[30:31]
	s_mov_b32 m0, s58
	s_nop 0
	global_load_lds_dwordx4 v152, s[0:1]
	s_add_i32 m0, s58, 0x2000
	s_nop 0
	global_load_lds_dwordx4 v156, s[0:1]
	s_waitcnt vmcnt(6)
	s_waitcnt lgkmcnt(0)
	v_mfma_f32_16x16x32_bf16 v[62:65], v[130:133], v[174:177], v[62:65]
	v_mfma_f32_16x16x32_bf16 v[62:65], v[134:137], v[178:181], v[62:65]
	s_barrier
	s_setprio 1
	v_mfma_f32_16x16x32_bf16 v[58:61], v[142:145], v[178:181], v[58:61]
	v_mfma_f32_16x16x32_bf16 v[58:61], v[138:141], v[174:177], v[58:61]
	v_mfma_f32_16x16x32_bf16 v[42:45], v[138:141], v[182:185], v[42:45]
	v_mfma_f32_16x16x32_bf16 v[42:45], v[142:145], v[186:189], v[42:45]
	v_mfma_f32_16x16x32_bf16 v[46:49], v[134:137], v[186:189], v[46:49]
	v_mfma_f32_16x16x32_bf16 v[46:49], v[130:133], v[182:185], v[46:49]
	v_mfma_f32_16x16x32_bf16 v[30:33], v[130:133], v[190:193], v[30:33]
	v_mfma_f32_16x16x32_bf16 v[30:33], v[134:137], v[204:207], v[30:33]
	v_mfma_f32_16x16x32_bf16 v[26:29], v[142:145], v[204:207], v[26:29]
	v_mfma_f32_16x16x32_bf16 v[26:29], v[138:141], v[190:193], v[26:29]
	v_mfma_f32_16x16x32_bf16 v[10:13], v[138:141], v[208:211], v[10:13]
	v_mfma_f32_16x16x32_bf16 v[10:13], v[142:145], v[212:215], v[10:13]
	v_mfma_f32_16x16x32_bf16 v[14:17], v[134:137], v[212:215], v[14:17]
	v_mfma_f32_16x16x32_bf16 v[14:17], v[130:133], v[208:211], v[14:17]
	v_mfma_f32_16x16x32_bf16 v[54:57], v[146:149], v[174:177], v[54:57]
	v_mfma_f32_16x16x32_bf16 v[54:57], v[162:165], v[178:181], v[54:57]
	v_mfma_f32_16x16x32_bf16 v[50:53], v[170:173], v[178:181], v[50:53]
	v_mfma_f32_16x16x32_bf16 v[50:53], v[166:169], v[174:177], v[50:53]
	v_mfma_f32_16x16x32_bf16 v[34:37], v[166:169], v[182:185], v[34:37]
	v_mfma_f32_16x16x32_bf16 v[34:37], v[170:173], v[186:189], v[34:37]
	v_mfma_f32_16x16x32_bf16 v[38:41], v[162:165], v[186:189], v[38:41]
	v_mfma_f32_16x16x32_bf16 v[38:41], v[146:149], v[182:185], v[38:41]
	v_mfma_f32_16x16x32_bf16 v[22:25], v[146:149], v[190:193], v[22:25]
	v_mfma_f32_16x16x32_bf16 v[22:25], v[162:165], v[204:207], v[22:25]
	v_mfma_f32_16x16x32_bf16 v[18:21], v[170:173], v[204:207], v[18:21]
	v_mfma_f32_16x16x32_bf16 v[18:21], v[166:169], v[190:193], v[18:21]
	v_mfma_f32_16x16x32_bf16 v[2:5], v[166:169], v[208:211], v[2:5]
	v_mfma_f32_16x16x32_bf16 v[2:5], v[170:173], v[212:215], v[2:5]
	v_mfma_f32_16x16x32_bf16 v[6:9], v[162:165], v[212:215], v[6:9]
	v_mfma_f32_16x16x32_bf16 v[6:9], v[146:149], v[208:211], v[6:9]
	s_setprio 0
	s_barrier
	s_mov_b32 m0, s38
	s_nop 0
	global_load_lds_dwordx4 v150, s[34:35]
	s_mov_b32 m0, s39
	s_nop 0
	global_load_lds_dwordx4 v154, s[34:35]
	ds_read_b128 v[174:177], v225 offset:32768
	ds_read_b128 v[178:181], v225 offset:33792
	ds_read_b128 v[182:185], v225 offset:34816
	ds_read_b128 v[186:189], v225 offset:35840
	ds_read_b128 v[190:193], v225 offset:36864
	ds_read_b128 v[204:207], v225 offset:37888
	ds_read_b128 v[208:211], v225 offset:38912
	ds_read_b128 v[212:215], v225 offset:39936
	ds_read_b128 v[130:133], v224 offset:32768
	ds_read_b128 v[134:137], v224 offset:33792
	ds_read_b128 v[138:141], v224 offset:34816
	ds_read_b128 v[142:145], v224 offset:35840
	ds_read_b128 v[146:149], v224 offset:49152
	ds_read_b128 v[162:165], v224 offset:50176
	ds_read_b128 v[166:169], v224 offset:51200
	ds_read_b128 v[170:173], v224 offset:52224
	s_add_i32 s58, 0, 0x18000
	s_add_i32 s59, 0, 0x1c000
	s_add_u32 s0, s34, 0x4000
	s_addc_u32 s1, s35, 0
	s_mov_b32 m0, s40
	s_nop 0
	global_load_lds_dwordx4 v150, s[0:1]
	s_mov_b32 m0, s41
	s_nop 0
	global_load_lds_dwordx4 v154, s[0:1]
	s_waitcnt vmcnt(8)
	s_waitcnt lgkmcnt(0)
	v_mfma_f32_16x16x32_bf16 v[126:129], v[130:133], v[174:177], v[126:129]
	v_mfma_f32_16x16x32_bf16 v[126:129], v[134:137], v[178:181], v[126:129]
	s_barrier
	s_setprio 1
	v_mfma_f32_16x16x32_bf16 v[122:125], v[142:145], v[178:181], v[122:125]
	v_mfma_f32_16x16x32_bf16 v[122:125], v[138:141], v[174:177], v[122:125]
	v_mfma_f32_16x16x32_bf16 v[106:109], v[138:141], v[182:185], v[106:109]
	v_mfma_f32_16x16x32_bf16 v[106:109], v[142:145], v[186:189], v[106:109]
	v_mfma_f32_16x16x32_bf16 v[110:113], v[134:137], v[186:189], v[110:113]
	v_mfma_f32_16x16x32_bf16 v[110:113], v[130:133], v[182:185], v[110:113]
	v_mfma_f32_16x16x32_bf16 v[94:97], v[130:133], v[190:193], v[94:97]
	v_mfma_f32_16x16x32_bf16 v[94:97], v[134:137], v[204:207], v[94:97]
	v_mfma_f32_16x16x32_bf16 v[90:93], v[142:145], v[204:207], v[90:93]
	v_mfma_f32_16x16x32_bf16 v[90:93], v[138:141], v[190:193], v[90:93]
	v_mfma_f32_16x16x32_bf16 v[74:77], v[138:141], v[208:211], v[74:77]
	v_mfma_f32_16x16x32_bf16 v[74:77], v[142:145], v[212:215], v[74:77]
	v_mfma_f32_16x16x32_bf16 v[78:81], v[134:137], v[212:215], v[78:81]
	v_mfma_f32_16x16x32_bf16 v[78:81], v[130:133], v[208:211], v[78:81]
	v_mfma_f32_16x16x32_bf16 v[118:121], v[146:149], v[174:177], v[118:121]
	v_mfma_f32_16x16x32_bf16 v[118:121], v[162:165], v[178:181], v[118:121]
	v_mfma_f32_16x16x32_bf16 v[114:117], v[170:173], v[178:181], v[114:117]
	v_mfma_f32_16x16x32_bf16 v[114:117], v[166:169], v[174:177], v[114:117]
	v_mfma_f32_16x16x32_bf16 v[98:101], v[166:169], v[182:185], v[98:101]
	v_mfma_f32_16x16x32_bf16 v[98:101], v[170:173], v[186:189], v[98:101]
	v_mfma_f32_16x16x32_bf16 v[102:105], v[162:165], v[186:189], v[102:105]
	v_mfma_f32_16x16x32_bf16 v[102:105], v[146:149], v[182:185], v[102:105]
	v_mfma_f32_16x16x32_bf16 v[86:89], v[146:149], v[190:193], v[86:89]
	v_mfma_f32_16x16x32_bf16 v[86:89], v[162:165], v[204:207], v[86:89]
	v_mfma_f32_16x16x32_bf16 v[82:85], v[170:173], v[204:207], v[82:85]
	v_mfma_f32_16x16x32_bf16 v[82:85], v[166:169], v[190:193], v[82:85]
	v_mfma_f32_16x16x32_bf16 v[66:69], v[166:169], v[208:211], v[66:69]
	v_mfma_f32_16x16x32_bf16 v[66:69], v[170:173], v[212:215], v[66:69]
	v_mfma_f32_16x16x32_bf16 v[70:73], v[162:165], v[212:215], v[70:73]
	v_mfma_f32_16x16x32_bf16 v[70:73], v[146:149], v[208:211], v[70:73]
	s_setprio 0
	s_barrier
	ds_read_b128 v[174:177], v225 offset:49152
	ds_read_b128 v[178:181], v225 offset:50176
	ds_read_b128 v[182:185], v225 offset:51200
	ds_read_b128 v[186:189], v225 offset:52224
	ds_read_b128 v[190:193], v225 offset:53248
	ds_read_b128 v[204:207], v225 offset:54272
	ds_read_b128 v[208:211], v225 offset:55296
	ds_read_b128 v[212:215], v225 offset:56320
	s_add_i32 s0, s58, s15
	s_add_u32 vcc_lo, s30, s94
	s_addc_u32 vcc_hi, s31, s95
	s_mov_b32 m0, s0
	s_nop 0
	global_load_lds_dwordx4 v152, vcc
	s_add_i32 m0, s0, 0x2000
	s_add_u32 s0, s30, 0x80080
	s_addc_u32 s1, s31, 0
	s_add_i32 s30, s59, s15
	global_load_lds_dwordx4 v156, vcc
	s_mov_b32 m0, s30
	s_nop 0
	global_load_lds_dwordx4 v152, s[0:1]
	s_add_i32 m0, s30, 0x2000
	s_nop 0
	global_load_lds_dwordx4 v156, s[0:1]
	s_waitcnt vmcnt(6)
	s_waitcnt lgkmcnt(0)
	v_mfma_f32_16x16x32_bf16 v[62:65], v[130:133], v[174:177], v[62:65]
	v_mfma_f32_16x16x32_bf16 v[62:65], v[134:137], v[178:181], v[62:65]
	s_barrier
	s_setprio 1
	v_mfma_f32_16x16x32_bf16 v[58:61], v[142:145], v[178:181], v[58:61]
	v_mfma_f32_16x16x32_bf16 v[58:61], v[138:141], v[174:177], v[58:61]
	v_mfma_f32_16x16x32_bf16 v[42:45], v[138:141], v[182:185], v[42:45]
	v_mfma_f32_16x16x32_bf16 v[42:45], v[142:145], v[186:189], v[42:45]
	v_mfma_f32_16x16x32_bf16 v[46:49], v[134:137], v[186:189], v[46:49]
	v_mfma_f32_16x16x32_bf16 v[46:49], v[130:133], v[182:185], v[46:49]
	v_mfma_f32_16x16x32_bf16 v[30:33], v[130:133], v[190:193], v[30:33]
	v_mfma_f32_16x16x32_bf16 v[30:33], v[134:137], v[204:207], v[30:33]
	v_mfma_f32_16x16x32_bf16 v[26:29], v[142:145], v[204:207], v[26:29]
	v_mfma_f32_16x16x32_bf16 v[26:29], v[138:141], v[190:193], v[26:29]
	v_mfma_f32_16x16x32_bf16 v[10:13], v[138:141], v[208:211], v[10:13]
	v_mfma_f32_16x16x32_bf16 v[10:13], v[142:145], v[212:215], v[10:13]
	s_add_i32 s57, s57, 2
	v_mfma_f32_16x16x32_bf16 v[14:17], v[134:137], v[212:215], v[14:17]
	v_mfma_f32_16x16x32_bf16 v[14:17], v[130:133], v[208:211], v[14:17]
	s_add_u32 s50, s50, 0x100
	v_mfma_f32_16x16x32_bf16 v[54:57], v[146:149], v[174:177], v[54:57]
	v_mfma_f32_16x16x32_bf16 v[54:57], v[162:165], v[178:181], v[54:57]
	s_addc_u32 s51, s51, 0
	v_mfma_f32_16x16x32_bf16 v[50:53], v[170:173], v[178:181], v[50:53]
	v_mfma_f32_16x16x32_bf16 v[50:53], v[166:169], v[174:177], v[50:53]
	s_cmp_gt_u32 s57, 29
	v_mfma_f32_16x16x32_bf16 v[34:37], v[166:169], v[182:185], v[34:37]
	v_mfma_f32_16x16x32_bf16 v[34:37], v[170:173], v[186:189], v[34:37]
	s_mov_b64 s[0:1], s[4:5]
	v_mfma_f32_16x16x32_bf16 v[38:41], v[162:165], v[186:189], v[38:41]
	v_mfma_f32_16x16x32_bf16 v[38:41], v[146:149], v[182:185], v[38:41]
	v_mfma_f32_16x16x32_bf16 v[22:25], v[146:149], v[190:193], v[22:25]
	v_mfma_f32_16x16x32_bf16 v[22:25], v[162:165], v[204:207], v[22:25]
	v_mfma_f32_16x16x32_bf16 v[18:21], v[170:173], v[204:207], v[18:21]
	v_mfma_f32_16x16x32_bf16 v[18:21], v[166:169], v[190:193], v[18:21]
	v_mfma_f32_16x16x32_bf16 v[2:5], v[166:169], v[208:211], v[2:5]
	v_mfma_f32_16x16x32_bf16 v[2:5], v[170:173], v[212:215], v[2:5]
	v_mfma_f32_16x16x32_bf16 v[6:9], v[162:165], v[212:215], v[6:9]
	v_mfma_f32_16x16x32_bf16 v[6:9], v[146:149], v[208:211], v[6:9]
	s_setprio 0
	s_barrier
	s_cbranch_scc0 .LBB0_133

.Lrealign_1:
.LBB0_305:
	s_add_u32 vcc_lo, s0, 0xffffc000
	s_addc_u32 vcc_hi, s1, -1
	s_mov_b32 m0, s62
	s_nop 0
	global_load_lds_dwordx4 v178, vcc
	s_mov_b32 m0, s63
	s_nop 0
	global_load_lds_dwordx4 v180, vcc
	ds_read_b128 v[162:165], v227
	ds_read_b128 v[166:169], v227 offset:1024
	ds_read_b128 v[182:185], v227 offset:2048
	ds_read_b128 v[186:189], v227 offset:3072
	ds_read_b128 v[190:193], v227 offset:4096
	ds_read_b128 v[204:207], v227 offset:5120
	ds_read_b128 v[208:211], v227 offset:6144
	ds_read_b128 v[212:215], v227 offset:7168
	ds_read_b128 v[130:133], v226
	ds_read_b128 v[134:137], v226 offset:1024
	ds_read_b128 v[138:141], v226 offset:2048
	ds_read_b128 v[142:145], v226 offset:3072
	ds_read_b128 v[146:149], v226 offset:16384
	ds_read_b128 v[150:153], v226 offset:17408
	ds_read_b128 v[154:157], v226 offset:18432
	ds_read_b128 v[158:161], v226 offset:19456
	s_add_i32 s71, s38, 2
	s_add_u32 s4, s0, 0x100
	s_addc_u32 s5, s1, 0
	s_add_i32 s73, 0, 0x10000
	s_cmp_eq_u32 s37, s38
	s_cselect_b32 s41, s31, s5
	s_cselect_b32 s40, s30, s4
	s_cselect_b32 s39, s25, s70
	s_cselect_b32 s38, s27, s51
	s_add_i32 s75, 0, 0x14000
	s_add_i32 m0, s56, 0xc000
	s_nop 0
	global_load_lds_dwordx4 v178, s[0:1]
	s_add_i32 m0, s56, 0xe000
	s_nop 0
	global_load_lds_dwordx4 v180, s[0:1]
	s_waitcnt vmcnt(8)
	s_waitcnt lgkmcnt(0)
	v_mfma_f32_16x16x32_bf16 v[126:129], v[130:133], v[162:165], v[126:129]
	v_mfma_f32_16x16x32_bf16 v[126:129], v[134:137], v[166:169], v[126:129]
	s_barrier
	s_setprio 1
	v_mfma_f32_16x16x32_bf16 v[122:125], v[142:145], v[166:169], v[122:125]
	v_mfma_f32_16x16x32_bf16 v[122:125], v[138:141], v[162:165], v[122:125]
	v_mfma_f32_16x16x32_bf16 v[106:109], v[138:141], v[182:185], v[106:109]
	v_mfma_f32_16x16x32_bf16 v[106:109], v[142:145], v[186:189], v[106:109]
	v_mfma_f32_16x16x32_bf16 v[110:113], v[134:137], v[186:189], v[110:113]
	v_mfma_f32_16x16x32_bf16 v[110:113], v[130:133], v[182:185], v[110:113]
	v_mfma_f32_16x16x32_bf16 v[94:97], v[130:133], v[190:193], v[94:97]
	v_mfma_f32_16x16x32_bf16 v[94:97], v[134:137], v[204:207], v[94:97]
	v_mfma_f32_16x16x32_bf16 v[90:93], v[142:145], v[204:207], v[90:93]
	v_mfma_f32_16x16x32_bf16 v[90:93], v[138:141], v[190:193], v[90:93]
	v_mfma_f32_16x16x32_bf16 v[74:77], v[138:141], v[208:211], v[74:77]
	v_mfma_f32_16x16x32_bf16 v[74:77], v[142:145], v[212:215], v[74:77]
	v_mfma_f32_16x16x32_bf16 v[78:81], v[134:137], v[212:215], v[78:81]
	v_mfma_f32_16x16x32_bf16 v[78:81], v[130:133], v[208:211], v[78:81]
	v_mfma_f32_16x16x32_bf16 v[118:121], v[146:149], v[162:165], v[118:121]
	v_mfma_f32_16x16x32_bf16 v[118:121], v[150:153], v[166:169], v[118:121]
	v_mfma_f32_16x16x32_bf16 v[114:117], v[158:161], v[166:169], v[114:117]
	v_mfma_f32_16x16x32_bf16 v[114:117], v[154:157], v[162:165], v[114:117]
	v_mfma_f32_16x16x32_bf16 v[98:101], v[154:157], v[182:185], v[98:101]
	v_mfma_f32_16x16x32_bf16 v[98:101], v[158:161], v[186:189], v[98:101]
	v_mfma_f32_16x16x32_bf16 v[102:105], v[150:153], v[186:189], v[102:105]
	v_mfma_f32_16x16x32_bf16 v[102:105], v[146:149], v[182:185], v[102:105]
	v_mfma_f32_16x16x32_bf16 v[86:89], v[146:149], v[190:193], v[86:89]
	v_mfma_f32_16x16x32_bf16 v[86:89], v[150:153], v[204:207], v[86:89]
	v_mfma_f32_16x16x32_bf16 v[82:85], v[158:161], v[204:207], v[82:85]
	v_mfma_f32_16x16x32_bf16 v[82:85], v[154:157], v[190:193], v[82:85]
	v_mfma_f32_16x16x32_bf16 v[66:69], v[154:157], v[208:211], v[66:69]
	v_mfma_f32_16x16x32_bf16 v[66:69], v[158:161], v[212:215], v[66:69]
	v_mfma_f32_16x16x32_bf16 v[70:73], v[150:153], v[212:215], v[70:73]
	v_mfma_f32_16x16x32_bf16 v[70:73], v[146:149], v[208:211], v[70:73]
	s_setprio 0
	s_barrier
	ds_read_b128 v[162:165], v227 offset:16384
	ds_read_b128 v[166:169], v227 offset:17408
	ds_read_b128 v[182:185], v227 offset:18432
	ds_read_b128 v[186:189], v227 offset:19456
	ds_read_b128 v[190:193], v227 offset:20480
	ds_read_b128 v[204:207], v227 offset:21504
	ds_read_b128 v[208:211], v227 offset:22528
	ds_read_b128 v[212:215], v227 offset:23552
	s_add_i32 s0, s73, s15
	s_mov_b32 m0, s0
	s_nop 0
	global_load_lds_dwordx4 v172, s[38:39]
	s_add_i32 m0, s0, 0x2000
	s_add_u32 s0, s38, 0x80000
	s_addc_u32 s1, s39, 0
	s_add_i32 s73, s75, s15
	global_load_lds_dwordx4 v176, s[38:39]
	s_mov_b32 m0, s73
	s_nop 0
	global_load_lds_dwordx4 v172, s[0:1]
	s_add_i32 m0, s73, 0x2000
	s_nop 0
	global_load_lds_dwordx4 v176, s[0:1]
	s_waitcnt vmcnt(6)
	s_waitcnt lgkmcnt(0)
	v_mfma_f32_16x16x32_bf16 v[62:65], v[130:133], v[162:165], v[62:65]
	v_mfma_f32_16x16x32_bf16 v[62:65], v[134:137], v[166:169], v[62:65]
	s_barrier
	s_setprio 1
	v_mfma_f32_16x16x32_bf16 v[58:61], v[142:145], v[166:169], v[58:61]
	v_mfma_f32_16x16x32_bf16 v[58:61], v[138:141], v[162:165], v[58:61]
	v_mfma_f32_16x16x32_bf16 v[42:45], v[138:141], v[182:185], v[42:45]
	v_mfma_f32_16x16x32_bf16 v[42:45], v[142:145], v[186:189], v[42:45]
	v_mfma_f32_16x16x32_bf16 v[46:49], v[134:137], v[186:189], v[46:49]
	v_mfma_f32_16x16x32_bf16 v[46:49], v[130:133], v[182:185], v[46:49]
	v_mfma_f32_16x16x32_bf16 v[30:33], v[130:133], v[190:193], v[30:33]
	v_mfma_f32_16x16x32_bf16 v[30:33], v[134:137], v[204:207], v[30:33]
	v_mfma_f32_16x16x32_bf16 v[26:29], v[142:145], v[204:207], v[26:29]
	v_mfma_f32_16x16x32_bf16 v[26:29], v[138:141], v[190:193], v[26:29]
	v_mfma_f32_16x16x32_bf16 v[10:13], v[138:141], v[208:211], v[10:13]
	v_mfma_f32_16x16x32_bf16 v[10:13], v[142:145], v[212:215], v[10:13]
	v_mfma_f32_16x16x32_bf16 v[14:17], v[134:137], v[212:215], v[14:17]
	v_mfma_f32_16x16x32_bf16 v[14:17], v[130:133], v[208:211], v[14:17]
	v_mfma_f32_16x16x32_bf16 v[54:57], v[146:149], v[162:165], v[54:57]
	v_mfma_f32_16x16x32_bf16 v[54:57], v[150:153], v[166:169], v[54:57]
	v_mfma_f32_16x16x32_bf16 v[50:53], v[158:161], v[166:169], v[50:53]
	v_mfma_f32_16x16x32_bf16 v[50:53], v[154:157], v[162:165], v[50:53]
	v_mfma_f32_16x16x32_bf16 v[34:37], v[154:157], v[182:185], v[34:37]
	v_mfma_f32_16x16x32_bf16 v[34:37], v[158:161], v[186:189], v[34:37]
	v_mfma_f32_16x16x32_bf16 v[38:41], v[150:153], v[186:189], v[38:41]
	v_mfma_f32_16x16x32_bf16 v[38:41], v[146:149], v[182:185], v[38:41]
	v_mfma_f32_16x16x32_bf16 v[22:25], v[146:149], v[190:193], v[22:25]
	v_mfma_f32_16x16x32_bf16 v[22:25], v[150:153], v[204:207], v[22:25]
	v_mfma_f32_16x16x32_bf16 v[18:21], v[158:161], v[204:207], v[18:21]
	v_mfma_f32_16x16x32_bf16 v[18:21], v[154:157], v[190:193], v[18:21]
	v_mfma_f32_16x16x32_bf16 v[2:5], v[154:157], v[208:211], v[2:5]
	v_mfma_f32_16x16x32_bf16 v[2:5], v[158:161], v[212:215], v[2:5]
	v_mfma_f32_16x16x32_bf16 v[6:9], v[150:153], v[212:215], v[6:9]
	v_mfma_f32_16x16x32_bf16 v[6:9], v[146:149], v[208:211], v[6:9]
	s_setprio 0
	s_barrier
	s_mov_b32 m0, s56
	s_nop 0
	global_load_lds_dwordx4 v170, s[40:41]
	s_mov_b32 m0, s57
	s_nop 0
	global_load_lds_dwordx4 v174, s[40:41]
	ds_read_b128 v[162:165], v227 offset:32768
	ds_read_b128 v[166:169], v227 offset:33792
	ds_read_b128 v[182:185], v227 offset:34816
	ds_read_b128 v[186:189], v227 offset:35840
	ds_read_b128 v[190:193], v227 offset:36864
	ds_read_b128 v[204:207], v227 offset:37888
	ds_read_b128 v[208:211], v227 offset:38912
	ds_read_b128 v[212:215], v227 offset:39936
	ds_read_b128 v[130:133], v226 offset:32768
	ds_read_b128 v[134:137], v226 offset:33792
	ds_read_b128 v[138:141], v226 offset:34816
	ds_read_b128 v[142:145], v226 offset:35840
	ds_read_b128 v[146:149], v226 offset:49152
	ds_read_b128 v[150:153], v226 offset:50176
	ds_read_b128 v[154:157], v226 offset:51200
	ds_read_b128 v[158:161], v226 offset:52224
	s_add_i32 s73, 0, 0x18000
	s_add_i32 s75, 0, 0x1c000
	s_add_u32 s0, s40, 0x4000
	s_addc_u32 s1, s41, 0
	s_mov_b32 m0, s58
	s_nop 0
	global_load_lds_dwordx4 v170, s[0:1]
	s_mov_b32 m0, s59
	s_nop 0
	global_load_lds_dwordx4 v174, s[0:1]
	s_waitcnt vmcnt(8)
	s_waitcnt lgkmcnt(0)
	v_mfma_f32_16x16x32_bf16 v[126:129], v[130:133], v[162:165], v[126:129]
	v_mfma_f32_16x16x32_bf16 v[126:129], v[134:137], v[166:169], v[126:129]
	s_barrier
	s_setprio 1
	v_mfma_f32_16x16x32_bf16 v[122:125], v[142:145], v[166:169], v[122:125]
	v_mfma_f32_16x16x32_bf16 v[122:125], v[138:141], v[162:165], v[122:125]
	v_mfma_f32_16x16x32_bf16 v[106:109], v[138:141], v[182:185], v[106:109]
	v_mfma_f32_16x16x32_bf16 v[106:109], v[142:145], v[186:189], v[106:109]
	v_mfma_f32_16x16x32_bf16 v[110:113], v[134:137], v[186:189], v[110:113]
	v_mfma_f32_16x16x32_bf16 v[110:113], v[130:133], v[182:185], v[110:113]
	v_mfma_f32_16x16x32_bf16 v[94:97], v[130:133], v[190:193], v[94:97]
	v_mfma_f32_16x16x32_bf16 v[94:97], v[134:137], v[204:207], v[94:97]
	v_mfma_f32_16x16x32_bf16 v[90:93], v[142:145], v[204:207], v[90:93]
	v_mfma_f32_16x16x32_bf16 v[90:93], v[138:141], v[190:193], v[90:93]
	v_mfma_f32_16x16x32_bf16 v[74:77], v[138:141], v[208:211], v[74:77]
	v_mfma_f32_16x16x32_bf16 v[74:77], v[142:145], v[212:215], v[74:77]
	v_mfma_f32_16x16x32_bf16 v[78:81], v[134:137], v[212:215], v[78:81]
	v_mfma_f32_16x16x32_bf16 v[78:81], v[130:133], v[208:211], v[78:81]
	v_mfma_f32_16x16x32_bf16 v[118:121], v[146:149], v[162:165], v[118:121]
	v_mfma_f32_16x16x32_bf16 v[118:121], v[150:153], v[166:169], v[118:121]
	v_mfma_f32_16x16x32_bf16 v[114:117], v[158:161], v[166:169], v[114:117]
	v_mfma_f32_16x16x32_bf16 v[114:117], v[154:157], v[162:165], v[114:117]
	v_mfma_f32_16x16x32_bf16 v[98:101], v[154:157], v[182:185], v[98:101]
	v_mfma_f32_16x16x32_bf16 v[98:101], v[158:161], v[186:189], v[98:101]
	v_mfma_f32_16x16x32_bf16 v[102:105], v[150:153], v[186:189], v[102:105]
	v_mfma_f32_16x16x32_bf16 v[102:105], v[146:149], v[182:185], v[102:105]
	v_mfma_f32_16x16x32_bf16 v[86:89], v[146:149], v[190:193], v[86:89]
	v_mfma_f32_16x16x32_bf16 v[86:89], v[150:153], v[204:207], v[86:89]
	v_mfma_f32_16x16x32_bf16 v[82:85], v[158:161], v[204:207], v[82:85]
	v_mfma_f32_16x16x32_bf16 v[82:85], v[154:157], v[190:193], v[82:85]
	v_mfma_f32_16x16x32_bf16 v[66:69], v[154:157], v[208:211], v[66:69]
	v_mfma_f32_16x16x32_bf16 v[66:69], v[158:161], v[212:215], v[66:69]
	v_mfma_f32_16x16x32_bf16 v[70:73], v[150:153], v[212:215], v[70:73]
	v_mfma_f32_16x16x32_bf16 v[70:73], v[146:149], v[208:211], v[70:73]
	s_setprio 0
	s_barrier
	ds_read_b128 v[162:165], v227 offset:49152
	ds_read_b128 v[166:169], v227 offset:50176
	ds_read_b128 v[182:185], v227 offset:51200
	ds_read_b128 v[186:189], v227 offset:52224
	ds_read_b128 v[190:193], v227 offset:53248
	ds_read_b128 v[204:207], v227 offset:54272
	ds_read_b128 v[208:211], v227 offset:55296
	ds_read_b128 v[212:215], v227 offset:56320
	s_add_i32 s0, s73, s15
	s_add_u32 vcc_lo, s38, s94
	s_addc_u32 vcc_hi, s39, s95
	s_mov_b32 m0, s0
	s_nop 0
	global_load_lds_dwordx4 v172, vcc
	s_add_i32 m0, s0, 0x2000
	s_add_u32 s0, s38, 0x80080
	s_addc_u32 s1, s39, 0
	s_add_i32 s38, s75, s15
	global_load_lds_dwordx4 v176, vcc
	s_mov_b32 m0, s38
	s_nop 0
	global_load_lds_dwordx4 v172, s[0:1]
	s_add_i32 m0, s38, 0x2000
	s_nop 0
	global_load_lds_dwordx4 v176, s[0:1]
	s_waitcnt vmcnt(6)
	s_waitcnt lgkmcnt(0)
	v_mfma_f32_16x16x32_bf16 v[62:65], v[130:133], v[162:165], v[62:65]
	v_mfma_f32_16x16x32_bf16 v[62:65], v[134:137], v[166:169], v[62:65]
	s_barrier
	s_setprio 1
	v_mfma_f32_16x16x32_bf16 v[58:61], v[142:145], v[166:169], v[58:61]
	v_mfma_f32_16x16x32_bf16 v[58:61], v[138:141], v[162:165], v[58:61]
	v_mfma_f32_16x16x32_bf16 v[42:45], v[138:141], v[182:185], v[42:45]
	v_mfma_f32_16x16x32_bf16 v[42:45], v[142:145], v[186:189], v[42:45]
	v_mfma_f32_16x16x32_bf16 v[46:49], v[134:137], v[186:189], v[46:49]
	v_mfma_f32_16x16x32_bf16 v[46:49], v[130:133], v[182:185], v[46:49]
	v_mfma_f32_16x16x32_bf16 v[30:33], v[130:133], v[190:193], v[30:33]
	v_mfma_f32_16x16x32_bf16 v[30:33], v[134:137], v[204:207], v[30:33]
	v_mfma_f32_16x16x32_bf16 v[26:29], v[142:145], v[204:207], v[26:29]
	v_mfma_f32_16x16x32_bf16 v[26:29], v[138:141], v[190:193], v[26:29]
	v_mfma_f32_16x16x32_bf16 v[10:13], v[138:141], v[208:211], v[10:13]
	v_mfma_f32_16x16x32_bf16 v[10:13], v[142:145], v[212:215], v[10:13]
	s_add_u32 s51, s51, 0x100
	v_mfma_f32_16x16x32_bf16 v[14:17], v[134:137], v[212:215], v[14:17]
	v_mfma_f32_16x16x32_bf16 v[14:17], v[130:133], v[208:211], v[14:17]
	s_addc_u32 s70, s70, 0
	v_mfma_f32_16x16x32_bf16 v[54:57], v[146:149], v[162:165], v[54:57]
	v_mfma_f32_16x16x32_bf16 v[54:57], v[150:153], v[166:169], v[54:57]
	s_cmp_ge_i32 s71, s35
	v_mfma_f32_16x16x32_bf16 v[50:53], v[158:161], v[166:169], v[50:53]
	v_mfma_f32_16x16x32_bf16 v[50:53], v[154:157], v[162:165], v[50:53]
	s_mov_b64 s[0:1], s[4:5]
	v_mfma_f32_16x16x32_bf16 v[34:37], v[154:157], v[182:185], v[34:37]
	v_mfma_f32_16x16x32_bf16 v[34:37], v[158:161], v[186:189], v[34:37]
	s_mov_b32 s38, s71
	v_mfma_f32_16x16x32_bf16 v[38:41], v[150:153], v[186:189], v[38:41]
	v_mfma_f32_16x16x32_bf16 v[38:41], v[146:149], v[182:185], v[38:41]
	v_mfma_f32_16x16x32_bf16 v[22:25], v[146:149], v[190:193], v[22:25]
	v_mfma_f32_16x16x32_bf16 v[22:25], v[150:153], v[204:207], v[22:25]
	v_mfma_f32_16x16x32_bf16 v[18:21], v[158:161], v[204:207], v[18:21]
	v_mfma_f32_16x16x32_bf16 v[18:21], v[154:157], v[190:193], v[18:21]
	v_mfma_f32_16x16x32_bf16 v[2:5], v[154:157], v[208:211], v[2:5]
	v_mfma_f32_16x16x32_bf16 v[2:5], v[158:161], v[212:215], v[2:5]
	v_mfma_f32_16x16x32_bf16 v[6:9], v[150:153], v[212:215], v[6:9]
	v_mfma_f32_16x16x32_bf16 v[6:9], v[146:149], v[208:211], v[6:9]
	s_setprio 0
	s_barrier
	s_cbranch_scc0 .LBB0_305
	s_movk_i32 s51, 0x2000
	s_mov_b32 s73, 0x10000
	s_mov_b32 s75, 0x12000
	s_and_b64 vcc, exec, s[16:17]
	s_cbranch_vccz .LBB0_308

.Lrealign_2:
.LBB0_530:
	s_add_u32 vcc_lo, s14, 0xfff80000
	s_addc_u32 vcc_hi, s15, -1
	s_mov_b32 m0, s27
	s_nop 0
	global_load_lds_dwordx4 v138, vcc
	s_mov_b32 m0, s28
	s_nop 0
	global_load_lds_dwordx4 v140, vcc
	ds_read_b128 v[184:187], v151
	ds_read_b128 v[188:191], v151 offset:1024
	ds_read_b128 v[204:207], v151 offset:2048
	ds_read_b128 v[208:211], v151 offset:3072
	ds_read_b128 v[212:215], v151 offset:4096
	ds_read_b128 v[216:219], v151 offset:5120
	ds_read_b128 v[220:223], v151 offset:6144
	ds_read_b128 v[224:227], v151 offset:7168
	ds_read_b128 v[152:155], v145
	ds_read_b128 v[156:159], v145 offset:1024
	ds_read_b128 v[160:163], v145 offset:2048
	ds_read_b128 v[164:167], v145 offset:3072
	ds_read_b128 v[168:171], v145 offset:16384
	ds_read_b128 v[172:175], v145 offset:17408
	ds_read_b128 v[176:179], v145 offset:18432
	ds_read_b128 v[180:183], v145 offset:19456
	s_add_u32 s16, s14, 0xfff80080
	s_addc_u32 s17, s15, -1
	s_add_i32 s40, 0, 0x10000
	s_cmp_eq_u32 s39, 28
	s_cselect_b32 s19, s34, s17
	s_cselect_b32 s18, s35, s16
	s_cselect_b32 s17, s9, s38
	s_cselect_b32 s16, s36, s37
	s_add_i32 s42, 0, 0x14000
	s_add_i32 m0, s23, 0xc000
	s_nop 0
	global_load_lds_dwordx4 v138, s[14:15]
	s_add_i32 m0, s23, 0xe000
	s_nop 0
	global_load_lds_dwordx4 v140, s[14:15]
	s_waitcnt vmcnt(8)
	s_waitcnt lgkmcnt(0)
	v_mfma_f32_16x16x32_bf16 v[126:129], v[152:155], v[184:187], v[126:129]
	v_mfma_f32_16x16x32_bf16 v[126:129], v[156:159], v[188:191], v[126:129]
	s_barrier
	s_setprio 1
	v_mfma_f32_16x16x32_bf16 v[122:125], v[164:167], v[188:191], v[122:125]
	v_mfma_f32_16x16x32_bf16 v[122:125], v[160:163], v[184:187], v[122:125]
	v_mfma_f32_16x16x32_bf16 v[106:109], v[160:163], v[204:207], v[106:109]
	v_mfma_f32_16x16x32_bf16 v[106:109], v[164:167], v[208:211], v[106:109]
	v_mfma_f32_16x16x32_bf16 v[110:113], v[156:159], v[208:211], v[110:113]
	v_mfma_f32_16x16x32_bf16 v[110:113], v[152:155], v[204:207], v[110:113]
	v_mfma_f32_16x16x32_bf16 v[94:97], v[152:155], v[212:215], v[94:97]
	v_mfma_f32_16x16x32_bf16 v[94:97], v[156:159], v[216:219], v[94:97]
	v_mfma_f32_16x16x32_bf16 v[90:93], v[164:167], v[216:219], v[90:93]
	v_mfma_f32_16x16x32_bf16 v[90:93], v[160:163], v[212:215], v[90:93]
	v_mfma_f32_16x16x32_bf16 v[74:77], v[160:163], v[220:223], v[74:77]
	v_mfma_f32_16x16x32_bf16 v[74:77], v[164:167], v[224:227], v[74:77]
	v_mfma_f32_16x16x32_bf16 v[78:81], v[156:159], v[224:227], v[78:81]
	v_mfma_f32_16x16x32_bf16 v[78:81], v[152:155], v[220:223], v[78:81]
	v_mfma_f32_16x16x32_bf16 v[118:121], v[168:171], v[184:187], v[118:121]
	v_mfma_f32_16x16x32_bf16 v[118:121], v[172:175], v[188:191], v[118:121]
	v_mfma_f32_16x16x32_bf16 v[114:117], v[180:183], v[188:191], v[114:117]
	v_mfma_f32_16x16x32_bf16 v[114:117], v[176:179], v[184:187], v[114:117]
	v_mfma_f32_16x16x32_bf16 v[98:101], v[176:179], v[204:207], v[98:101]
	v_mfma_f32_16x16x32_bf16 v[98:101], v[180:183], v[208:211], v[98:101]
	v_mfma_f32_16x16x32_bf16 v[102:105], v[172:175], v[208:211], v[102:105]
	v_mfma_f32_16x16x32_bf16 v[102:105], v[168:171], v[204:207], v[102:105]
	v_mfma_f32_16x16x32_bf16 v[86:89], v[168:171], v[212:215], v[86:89]
	v_mfma_f32_16x16x32_bf16 v[86:89], v[172:175], v[216:219], v[86:89]
	v_mfma_f32_16x16x32_bf16 v[82:85], v[180:183], v[216:219], v[82:85]
	v_mfma_f32_16x16x32_bf16 v[82:85], v[176:179], v[212:215], v[82:85]
	v_mfma_f32_16x16x32_bf16 v[66:69], v[176:179], v[220:223], v[66:69]
	v_mfma_f32_16x16x32_bf16 v[66:69], v[180:183], v[224:227], v[66:69]
	v_mfma_f32_16x16x32_bf16 v[70:73], v[172:175], v[224:227], v[70:73]
	v_mfma_f32_16x16x32_bf16 v[70:73], v[168:171], v[220:223], v[70:73]
	s_setprio 0
	s_barrier
	ds_read_b128 v[184:187], v151 offset:16384
	ds_read_b128 v[188:191], v151 offset:17408
	ds_read_b128 v[204:207], v151 offset:18432
	ds_read_b128 v[208:211], v151 offset:19456
	ds_read_b128 v[212:215], v151 offset:20480
	ds_read_b128 v[216:219], v151 offset:21504
	ds_read_b128 v[220:223], v151 offset:22528
	ds_read_b128 v[224:227], v151 offset:23552
	s_add_i32 s40, s40, s22
	s_mov_b32 m0, s40
	s_nop 0
	global_load_lds_dwordx4 v134, s[16:17]
	s_add_i32 m0, s40, 0x2000
	s_add_u32 s40, s16, 0x80000
	s_addc_u32 s41, s17, 0
	s_add_i32 s42, s42, s22
	global_load_lds_dwordx4 v130, s[16:17]
	s_mov_b32 m0, s42
	s_nop 0
	global_load_lds_dwordx4 v134, s[40:41]
	s_add_i32 m0, s42, 0x2000
	s_nop 0
	global_load_lds_dwordx4 v130, s[40:41]
	s_waitcnt vmcnt(6)
	s_waitcnt lgkmcnt(0)
	v_mfma_f32_16x16x32_bf16 v[62:65], v[152:155], v[184:187], v[62:65]
	v_mfma_f32_16x16x32_bf16 v[62:65], v[156:159], v[188:191], v[62:65]
	s_barrier
	s_setprio 1
	v_mfma_f32_16x16x32_bf16 v[58:61], v[164:167], v[188:191], v[58:61]
	v_mfma_f32_16x16x32_bf16 v[58:61], v[160:163], v[184:187], v[58:61]
	v_mfma_f32_16x16x32_bf16 v[42:45], v[160:163], v[204:207], v[42:45]
	v_mfma_f32_16x16x32_bf16 v[42:45], v[164:167], v[208:211], v[42:45]
	v_mfma_f32_16x16x32_bf16 v[46:49], v[156:159], v[208:211], v[46:49]
	v_mfma_f32_16x16x32_bf16 v[46:49], v[152:155], v[204:207], v[46:49]
	v_mfma_f32_16x16x32_bf16 v[30:33], v[152:155], v[212:215], v[30:33]
	v_mfma_f32_16x16x32_bf16 v[30:33], v[156:159], v[216:219], v[30:33]
	v_mfma_f32_16x16x32_bf16 v[26:29], v[164:167], v[216:219], v[26:29]
	v_mfma_f32_16x16x32_bf16 v[26:29], v[160:163], v[212:215], v[26:29]
	v_mfma_f32_16x16x32_bf16 v[10:13], v[160:163], v[220:223], v[10:13]
	v_mfma_f32_16x16x32_bf16 v[10:13], v[164:167], v[224:227], v[10:13]
	v_mfma_f32_16x16x32_bf16 v[14:17], v[156:159], v[224:227], v[14:17]
	v_mfma_f32_16x16x32_bf16 v[14:17], v[152:155], v[220:223], v[14:17]
	v_mfma_f32_16x16x32_bf16 v[54:57], v[168:171], v[184:187], v[54:57]
	v_mfma_f32_16x16x32_bf16 v[54:57], v[172:175], v[188:191], v[54:57]
	v_mfma_f32_16x16x32_bf16 v[50:53], v[180:183], v[188:191], v[50:53]
	v_mfma_f32_16x16x32_bf16 v[50:53], v[176:179], v[184:187], v[50:53]
	v_mfma_f32_16x16x32_bf16 v[34:37], v[176:179], v[204:207], v[34:37]
	v_mfma_f32_16x16x32_bf16 v[34:37], v[180:183], v[208:211], v[34:37]
	v_mfma_f32_16x16x32_bf16 v[38:41], v[172:175], v[208:211], v[38:41]
	v_mfma_f32_16x16x32_bf16 v[38:41], v[168:171], v[204:207], v[38:41]
	v_mfma_f32_16x16x32_bf16 v[22:25], v[168:171], v[212:215], v[22:25]
	v_mfma_f32_16x16x32_bf16 v[22:25], v[172:175], v[216:219], v[22:25]
	v_mfma_f32_16x16x32_bf16 v[18:21], v[180:183], v[216:219], v[18:21]
	v_mfma_f32_16x16x32_bf16 v[18:21], v[176:179], v[212:215], v[18:21]
	v_mfma_f32_16x16x32_bf16 v[2:5], v[176:179], v[220:223], v[2:5]
	v_mfma_f32_16x16x32_bf16 v[2:5], v[180:183], v[224:227], v[2:5]
	v_mfma_f32_16x16x32_bf16 v[6:9], v[172:175], v[224:227], v[6:9]
	v_mfma_f32_16x16x32_bf16 v[6:9], v[168:171], v[220:223], v[6:9]
	s_setprio 0
	s_barrier
	s_mov_b32 m0, s23
	s_nop 0
	global_load_lds_dwordx4 v136, s[18:19]
	s_mov_b32 m0, s24
	s_nop 0
	global_load_lds_dwordx4 v132, s[18:19]
	ds_read_b128 v[184:187], v151 offset:32768
	ds_read_b128 v[188:191], v151 offset:33792
	ds_read_b128 v[204:207], v151 offset:34816
	ds_read_b128 v[208:211], v151 offset:35840
	ds_read_b128 v[212:215], v151 offset:36864
	ds_read_b128 v[216:219], v151 offset:37888
	ds_read_b128 v[220:223], v151 offset:38912
	ds_read_b128 v[224:227], v151 offset:39936
	ds_read_b128 v[152:155], v145 offset:32768
	ds_read_b128 v[156:159], v145 offset:33792
	ds_read_b128 v[160:163], v145 offset:34816
	ds_read_b128 v[164:167], v145 offset:35840
	ds_read_b128 v[168:171], v145 offset:49152
	ds_read_b128 v[172:175], v145 offset:50176
	ds_read_b128 v[176:179], v145 offset:51200
	ds_read_b128 v[180:183], v145 offset:52224
	s_add_i32 s40, 0, 0x18000
	s_add_i32 s41, 0, 0x1c000
	s_add_u32 s18, s18, 0x80000
	s_addc_u32 s19, s19, 0
	s_mov_b32 m0, s25
	s_nop 0
	global_load_lds_dwordx4 v136, s[18:19]
	s_mov_b32 m0, s26
	s_nop 0
	global_load_lds_dwordx4 v132, s[18:19]
	s_waitcnt vmcnt(8)
	s_waitcnt lgkmcnt(0)
	v_mfma_f32_16x16x32_bf16 v[126:129], v[152:155], v[184:187], v[126:129]
	v_mfma_f32_16x16x32_bf16 v[126:129], v[156:159], v[188:191], v[126:129]
	s_barrier
	s_setprio 1
	v_mfma_f32_16x16x32_bf16 v[122:125], v[164:167], v[188:191], v[122:125]
	v_mfma_f32_16x16x32_bf16 v[122:125], v[160:163], v[184:187], v[122:125]
	v_mfma_f32_16x16x32_bf16 v[106:109], v[160:163], v[204:207], v[106:109]
	v_mfma_f32_16x16x32_bf16 v[106:109], v[164:167], v[208:211], v[106:109]
	v_mfma_f32_16x16x32_bf16 v[110:113], v[156:159], v[208:211], v[110:113]
	v_mfma_f32_16x16x32_bf16 v[110:113], v[152:155], v[204:207], v[110:113]
	v_mfma_f32_16x16x32_bf16 v[94:97], v[152:155], v[212:215], v[94:97]
	v_mfma_f32_16x16x32_bf16 v[94:97], v[156:159], v[216:219], v[94:97]
	v_mfma_f32_16x16x32_bf16 v[90:93], v[164:167], v[216:219], v[90:93]
	v_mfma_f32_16x16x32_bf16 v[90:93], v[160:163], v[212:215], v[90:93]
	v_mfma_f32_16x16x32_bf16 v[74:77], v[160:163], v[220:223], v[74:77]
	v_mfma_f32_16x16x32_bf16 v[74:77], v[164:167], v[224:227], v[74:77]
	v_mfma_f32_16x16x32_bf16 v[78:81], v[156:159], v[224:227], v[78:81]
	v_mfma_f32_16x16x32_bf16 v[78:81], v[152:155], v[220:223], v[78:81]
	v_mfma_f32_16x16x32_bf16 v[118:121], v[168:171], v[184:187], v[118:121]
	v_mfma_f32_16x16x32_bf16 v[118:121], v[172:175], v[188:191], v[118:121]
	v_mfma_f32_16x16x32_bf16 v[114:117], v[180:183], v[188:191], v[114:117]
	v_mfma_f32_16x16x32_bf16 v[114:117], v[176:179], v[184:187], v[114:117]
	v_mfma_f32_16x16x32_bf16 v[98:101], v[176:179], v[204:207], v[98:101]
	v_mfma_f32_16x16x32_bf16 v[98:101], v[180:183], v[208:211], v[98:101]
	v_mfma_f32_16x16x32_bf16 v[102:105], v[172:175], v[208:211], v[102:105]
	v_mfma_f32_16x16x32_bf16 v[102:105], v[168:171], v[204:207], v[102:105]
	v_mfma_f32_16x16x32_bf16 v[86:89], v[168:171], v[212:215], v[86:89]
	v_mfma_f32_16x16x32_bf16 v[86:89], v[172:175], v[216:219], v[86:89]
	v_mfma_f32_16x16x32_bf16 v[82:85], v[180:183], v[216:219], v[82:85]
	v_mfma_f32_16x16x32_bf16 v[82:85], v[176:179], v[212:215], v[82:85]
	v_mfma_f32_16x16x32_bf16 v[66:69], v[176:179], v[220:223], v[66:69]
	v_mfma_f32_16x16x32_bf16 v[66:69], v[180:183], v[224:227], v[66:69]
	v_mfma_f32_16x16x32_bf16 v[70:73], v[172:175], v[224:227], v[70:73]
	v_mfma_f32_16x16x32_bf16 v[70:73], v[168:171], v[220:223], v[70:73]
	s_setprio 0
	s_barrier
	ds_read_b128 v[184:187], v151 offset:49152
	ds_read_b128 v[188:191], v151 offset:50176
	ds_read_b128 v[204:207], v151 offset:51200
	ds_read_b128 v[208:211], v151 offset:52224
	ds_read_b128 v[212:215], v151 offset:53248
	ds_read_b128 v[216:219], v151 offset:54272
	ds_read_b128 v[220:223], v151 offset:55296
	ds_read_b128 v[224:227], v151 offset:56320
	s_add_i32 s18, s40, s22
	s_add_u32 vcc_lo, s16, s94
	s_addc_u32 vcc_hi, s17, s95
	s_mov_b32 m0, s18
	s_nop 0
	global_load_lds_dwordx4 v134, vcc
	s_add_i32 m0, s18, 0x2000
	s_add_u32 s16, s16, 0x80080
	s_addc_u32 s17, s17, 0
	s_add_i32 s18, s41, s22
	global_load_lds_dwordx4 v130, vcc
	s_mov_b32 m0, s18
	s_nop 0
	global_load_lds_dwordx4 v134, s[16:17]
	s_add_i32 m0, s18, 0x2000
	s_nop 0
	global_load_lds_dwordx4 v130, s[16:17]
	s_waitcnt vmcnt(6)
	s_waitcnt lgkmcnt(0)
	v_mfma_f32_16x16x32_bf16 v[62:65], v[152:155], v[184:187], v[62:65]
	v_mfma_f32_16x16x32_bf16 v[62:65], v[156:159], v[188:191], v[62:65]
	s_barrier
	s_setprio 1
	v_mfma_f32_16x16x32_bf16 v[58:61], v[164:167], v[188:191], v[58:61]
	v_mfma_f32_16x16x32_bf16 v[58:61], v[160:163], v[184:187], v[58:61]
	v_mfma_f32_16x16x32_bf16 v[42:45], v[160:163], v[204:207], v[42:45]
	v_mfma_f32_16x16x32_bf16 v[42:45], v[164:167], v[208:211], v[42:45]
	v_mfma_f32_16x16x32_bf16 v[46:49], v[156:159], v[208:211], v[46:49]
	v_mfma_f32_16x16x32_bf16 v[46:49], v[152:155], v[204:207], v[46:49]
	v_mfma_f32_16x16x32_bf16 v[30:33], v[152:155], v[212:215], v[30:33]
	v_mfma_f32_16x16x32_bf16 v[30:33], v[156:159], v[216:219], v[30:33]
	v_mfma_f32_16x16x32_bf16 v[26:29], v[164:167], v[216:219], v[26:29]
	v_mfma_f32_16x16x32_bf16 v[26:29], v[160:163], v[212:215], v[26:29]
	v_mfma_f32_16x16x32_bf16 v[10:13], v[160:163], v[220:223], v[10:13]
	v_mfma_f32_16x16x32_bf16 v[10:13], v[164:167], v[224:227], v[10:13]
	s_add_i32 s39, s39, 2
	v_mfma_f32_16x16x32_bf16 v[14:17], v[156:159], v[224:227], v[14:17]
	v_mfma_f32_16x16x32_bf16 v[14:17], v[152:155], v[220:223], v[14:17]
	s_add_u32 s14, s14, 0x100
	v_mfma_f32_16x16x32_bf16 v[54:57], v[168:171], v[184:187], v[54:57]
	v_mfma_f32_16x16x32_bf16 v[54:57], v[172:175], v[188:191], v[54:57]
	s_addc_u32 s15, s15, 0
	v_mfma_f32_16x16x32_bf16 v[50:53], v[180:183], v[188:191], v[50:53]
	v_mfma_f32_16x16x32_bf16 v[50:53], v[176:179], v[184:187], v[50:53]
	s_add_u32 s37, s37, 0x100
	v_mfma_f32_16x16x32_bf16 v[34:37], v[176:179], v[204:207], v[34:37]
	v_mfma_f32_16x16x32_bf16 v[34:37], v[180:183], v[208:211], v[34:37]
	s_addc_u32 s38, s38, 0
	v_mfma_f32_16x16x32_bf16 v[38:41], v[172:175], v[208:211], v[38:41]
	v_mfma_f32_16x16x32_bf16 v[38:41], v[168:171], v[204:207], v[38:41]
	s_cmp_gt_u32 s39, 29
	v_mfma_f32_16x16x32_bf16 v[22:25], v[168:171], v[212:215], v[22:25]
	v_mfma_f32_16x16x32_bf16 v[22:25], v[172:175], v[216:219], v[22:25]
	v_mfma_f32_16x16x32_bf16 v[18:21], v[180:183], v[216:219], v[18:21]
	v_mfma_f32_16x16x32_bf16 v[18:21], v[176:179], v[212:215], v[18:21]
	v_mfma_f32_16x16x32_bf16 v[2:5], v[176:179], v[220:223], v[2:5]
	v_mfma_f32_16x16x32_bf16 v[2:5], v[180:183], v[224:227], v[2:5]
	v_mfma_f32_16x16x32_bf16 v[6:9], v[172:175], v[224:227], v[6:9]
	v_mfma_f32_16x16x32_bf16 v[6:9], v[168:171], v[220:223], v[6:9]
	s_setprio 0
	s_barrier
	s_cbranch_scc0 .LBB0_530

.LBB0_769:
	s_sub_u32 vcc_lo, s22, s12
	s_subb_u32 vcc_hi, s23, 0
	s_mov_b32 m0, s37
	s_nop 0
	global_load_lds_dwordx4 v214, vcc
	s_mov_b32 m0, s38
	s_nop 0
	global_load_lds_dwordx4 v212, vcc
	ds_read_b128 v[164:167], v197
	ds_read_b128 v[168:171], v197 offset:1024
	ds_read_b128 v[172:175], v197 offset:2048
	ds_read_b128 v[176:179], v197 offset:3072
	ds_read_b128 v[180:183], v197 offset:4096
	ds_read_b128 v[184:187], v197 offset:5120
	ds_read_b128 v[188:191], v197 offset:6144
	ds_read_b128 v[216:219], v197 offset:7168
	ds_read_b128 v[132:135], v231
	ds_read_b128 v[136:139], v231 offset:1024
	ds_read_b128 v[140:143], v231 offset:2048
	ds_read_b128 v[144:147], v231 offset:3072
	ds_read_b128 v[148:151], v231 offset:16384
	ds_read_b128 v[152:155], v231 offset:17408
	ds_read_b128 v[156:159], v231 offset:18432
	ds_read_b128 v[160:163], v231 offset:19456
	s_add_u32 s24, s22, 0x80
	s_addc_u32 s25, s23, 0
	s_add_i32 s57, 0, 0x10000
	s_cmp_eq_u32 s53, s56
	s_cselect_b32 s25, s1, s25
	s_cselect_b32 s24, s0, s24
	s_cselect_b32 s59, s19, s55
	s_cselect_b32 s58, s18, s54
	s_add_i32 s60, 0, 0x14000
	s_add_i32 m0, s33, 0xc000
	s_nop 0
	global_load_lds_dwordx4 v214, s[22:23]
	s_add_i32 m0, s33, 0xe000
	s_nop 0
	global_load_lds_dwordx4 v212, s[22:23]
	s_waitcnt vmcnt(8)
	s_waitcnt lgkmcnt(0)
	v_mfma_f32_16x16x32_bf16 v[126:129], v[132:135], v[164:167], v[126:129]
	v_mfma_f32_16x16x32_bf16 v[126:129], v[136:139], v[168:171], v[126:129]
	s_barrier
	s_setprio 1
	v_mfma_f32_16x16x32_bf16 v[122:125], v[144:147], v[168:171], v[122:125]
	v_mfma_f32_16x16x32_bf16 v[122:125], v[140:143], v[164:167], v[122:125]
	v_mfma_f32_16x16x32_bf16 v[106:109], v[140:143], v[172:175], v[106:109]
	v_mfma_f32_16x16x32_bf16 v[106:109], v[144:147], v[176:179], v[106:109]
	v_mfma_f32_16x16x32_bf16 v[110:113], v[136:139], v[176:179], v[110:113]
	v_mfma_f32_16x16x32_bf16 v[110:113], v[132:135], v[172:175], v[110:113]
	v_mfma_f32_16x16x32_bf16 v[94:97], v[132:135], v[180:183], v[94:97]
	v_mfma_f32_16x16x32_bf16 v[94:97], v[136:139], v[184:187], v[94:97]
	v_mfma_f32_16x16x32_bf16 v[90:93], v[144:147], v[184:187], v[90:93]
	v_mfma_f32_16x16x32_bf16 v[90:93], v[140:143], v[180:183], v[90:93]
	v_mfma_f32_16x16x32_bf16 v[74:77], v[140:143], v[188:191], v[74:77]
	v_mfma_f32_16x16x32_bf16 v[74:77], v[144:147], v[216:219], v[74:77]
	v_mfma_f32_16x16x32_bf16 v[78:81], v[136:139], v[216:219], v[78:81]
	v_mfma_f32_16x16x32_bf16 v[78:81], v[132:135], v[188:191], v[78:81]
	v_mfma_f32_16x16x32_bf16 v[118:121], v[148:151], v[164:167], v[118:121]
	v_mfma_f32_16x16x32_bf16 v[118:121], v[152:155], v[168:171], v[118:121]
	v_mfma_f32_16x16x32_bf16 v[114:117], v[160:163], v[168:171], v[114:117]
	v_mfma_f32_16x16x32_bf16 v[114:117], v[156:159], v[164:167], v[114:117]
	v_mfma_f32_16x16x32_bf16 v[98:101], v[156:159], v[172:175], v[98:101]
	v_mfma_f32_16x16x32_bf16 v[98:101], v[160:163], v[176:179], v[98:101]
	v_mfma_f32_16x16x32_bf16 v[102:105], v[152:155], v[176:179], v[102:105]
	v_mfma_f32_16x16x32_bf16 v[102:105], v[148:151], v[172:175], v[102:105]
	v_mfma_f32_16x16x32_bf16 v[86:89], v[148:151], v[180:183], v[86:89]
	v_mfma_f32_16x16x32_bf16 v[86:89], v[152:155], v[184:187], v[86:89]
	v_mfma_f32_16x16x32_bf16 v[82:85], v[160:163], v[184:187], v[82:85]
	v_mfma_f32_16x16x32_bf16 v[82:85], v[156:159], v[180:183], v[82:85]
	v_mfma_f32_16x16x32_bf16 v[66:69], v[156:159], v[188:191], v[66:69]
	v_mfma_f32_16x16x32_bf16 v[66:69], v[160:163], v[216:219], v[66:69]
	v_mfma_f32_16x16x32_bf16 v[70:73], v[152:155], v[216:219], v[70:73]
	v_mfma_f32_16x16x32_bf16 v[70:73], v[148:151], v[188:191], v[70:73]
	s_setprio 0
	s_barrier
	ds_read_b128 v[164:167], v197 offset:16384
	ds_read_b128 v[168:171], v197 offset:17408
	ds_read_b128 v[172:175], v197 offset:18432
	ds_read_b128 v[176:179], v197 offset:19456
	ds_read_b128 v[180:183], v197 offset:20480
	ds_read_b128 v[184:187], v197 offset:21504
	ds_read_b128 v[188:191], v197 offset:22528
	ds_read_b128 v[216:219], v197 offset:23552
	s_add_i32 s57, s57, s26
	v_lshl_add_u64 v[192:193], s[58:59], 0, v[208:209]
	s_mov_b32 m0, s57
	s_nop 0
	global_load_lds_dwordx4 v208, s[58:59]
	s_add_i32 m0, s57, 0x2000
	v_lshl_add_u64 v[220:221], s[58:59], 0, v[204:205]
	s_add_u32 s58, s58, s12
	s_addc_u32 s59, s59, 0
	s_add_i32 s57, s60, s26
	global_load_lds_dwordx4 v[220:221], off
	v_lshl_add_u64 v[224:225], s[58:59], 0, v[208:209]
	s_mov_b32 m0, s57
	v_lshl_add_u64 v[226:227], s[58:59], 0, v[204:205]
	global_load_lds_dwordx4 v208, s[58:59]
	s_add_i32 m0, s57, 0x2000
	s_nop 0
	global_load_lds_dwordx4 v204, s[58:59]
	s_waitcnt vmcnt(6)
	s_waitcnt lgkmcnt(0)
	v_mfma_f32_16x16x32_bf16 v[62:65], v[132:135], v[164:167], v[62:65]
	v_mfma_f32_16x16x32_bf16 v[62:65], v[136:139], v[168:171], v[62:65]
	s_barrier
	s_setprio 1
	v_mfma_f32_16x16x32_bf16 v[58:61], v[144:147], v[168:171], v[58:61]
	v_mfma_f32_16x16x32_bf16 v[58:61], v[140:143], v[164:167], v[58:61]
	v_mfma_f32_16x16x32_bf16 v[42:45], v[140:143], v[172:175], v[42:45]
	v_mfma_f32_16x16x32_bf16 v[42:45], v[144:147], v[176:179], v[42:45]
	v_mfma_f32_16x16x32_bf16 v[46:49], v[136:139], v[176:179], v[46:49]
	v_mfma_f32_16x16x32_bf16 v[46:49], v[132:135], v[172:175], v[46:49]
	v_mfma_f32_16x16x32_bf16 v[30:33], v[132:135], v[180:183], v[30:33]
	v_mfma_f32_16x16x32_bf16 v[30:33], v[136:139], v[184:187], v[30:33]
	v_mfma_f32_16x16x32_bf16 v[26:29], v[144:147], v[184:187], v[26:29]
	v_mfma_f32_16x16x32_bf16 v[26:29], v[140:143], v[180:183], v[26:29]
	v_mfma_f32_16x16x32_bf16 v[10:13], v[140:143], v[188:191], v[10:13]
	v_mfma_f32_16x16x32_bf16 v[10:13], v[144:147], v[216:219], v[10:13]
	v_mfma_f32_16x16x32_bf16 v[14:17], v[136:139], v[216:219], v[14:17]
	v_mfma_f32_16x16x32_bf16 v[14:17], v[132:135], v[188:191], v[14:17]
	v_mfma_f32_16x16x32_bf16 v[54:57], v[148:151], v[164:167], v[54:57]
	v_mfma_f32_16x16x32_bf16 v[54:57], v[152:155], v[168:171], v[54:57]
	v_mfma_f32_16x16x32_bf16 v[50:53], v[160:163], v[168:171], v[50:53]
	v_mfma_f32_16x16x32_bf16 v[50:53], v[156:159], v[164:167], v[50:53]
	v_mfma_f32_16x16x32_bf16 v[34:37], v[156:159], v[172:175], v[34:37]
	v_mfma_f32_16x16x32_bf16 v[34:37], v[160:163], v[176:179], v[34:37]
	v_mfma_f32_16x16x32_bf16 v[38:41], v[152:155], v[176:179], v[38:41]
	v_mfma_f32_16x16x32_bf16 v[38:41], v[148:151], v[172:175], v[38:41]
	v_mfma_f32_16x16x32_bf16 v[22:25], v[148:151], v[180:183], v[22:25]
	v_mfma_f32_16x16x32_bf16 v[22:25], v[152:155], v[184:187], v[22:25]
	v_mfma_f32_16x16x32_bf16 v[18:21], v[160:163], v[184:187], v[18:21]
	v_mfma_f32_16x16x32_bf16 v[18:21], v[156:159], v[180:183], v[18:21]
	v_mfma_f32_16x16x32_bf16 v[2:5], v[156:159], v[188:191], v[2:5]
	v_mfma_f32_16x16x32_bf16 v[2:5], v[160:163], v[216:219], v[2:5]
	v_mfma_f32_16x16x32_bf16 v[6:9], v[152:155], v[216:219], v[6:9]
	v_mfma_f32_16x16x32_bf16 v[6:9], v[148:151], v[188:191], v[6:9]
	s_setprio 0
	s_barrier
	s_mov_b32 m0, s33
	s_nop 0
	global_load_lds_dwordx4 v210, s[24:25]
	s_mov_b32 m0, s34
	s_nop 0
	global_load_lds_dwordx4 v206, s[24:25]
	ds_read_b128 v[164:167], v197 offset:32768
	ds_read_b128 v[168:171], v197 offset:33792
	ds_read_b128 v[172:175], v197 offset:34816
	ds_read_b128 v[176:179], v197 offset:35840
	ds_read_b128 v[180:183], v197 offset:36864
	ds_read_b128 v[184:187], v197 offset:37888
	ds_read_b128 v[188:191], v197 offset:38912
	ds_read_b128 v[216:219], v197 offset:39936
	ds_read_b128 v[132:135], v231 offset:32768
	ds_read_b128 v[136:139], v231 offset:33792
	ds_read_b128 v[140:143], v231 offset:34816
	ds_read_b128 v[144:147], v231 offset:35840
	ds_read_b128 v[148:151], v231 offset:49152
	ds_read_b128 v[152:155], v231 offset:50176
	ds_read_b128 v[156:159], v231 offset:51200
	ds_read_b128 v[160:163], v231 offset:52224
	s_add_i32 s57, 0, 0x18000
	s_add_i32 s58, 0, 0x1c000
	s_add_u32 s24, s24, s12
	s_addc_u32 s25, s25, 0
	s_mov_b32 m0, s35
	s_nop 0
	global_load_lds_dwordx4 v210, s[24:25]
	s_mov_b32 m0, s36
	s_nop 0
	global_load_lds_dwordx4 v206, s[24:25]
	s_waitcnt vmcnt(8)
	s_waitcnt lgkmcnt(0)
	v_mfma_f32_16x16x32_bf16 v[126:129], v[132:135], v[164:167], v[126:129]
	v_mfma_f32_16x16x32_bf16 v[126:129], v[136:139], v[168:171], v[126:129]
	s_barrier
	s_setprio 1
	v_mfma_f32_16x16x32_bf16 v[122:125], v[144:147], v[168:171], v[122:125]
	v_mfma_f32_16x16x32_bf16 v[122:125], v[140:143], v[164:167], v[122:125]
	v_mfma_f32_16x16x32_bf16 v[106:109], v[140:143], v[172:175], v[106:109]
	v_mfma_f32_16x16x32_bf16 v[106:109], v[144:147], v[176:179], v[106:109]
	v_mfma_f32_16x16x32_bf16 v[110:113], v[136:139], v[176:179], v[110:113]
	v_mfma_f32_16x16x32_bf16 v[110:113], v[132:135], v[172:175], v[110:113]
	v_mfma_f32_16x16x32_bf16 v[94:97], v[132:135], v[180:183], v[94:97]
	v_mfma_f32_16x16x32_bf16 v[94:97], v[136:139], v[184:187], v[94:97]
	v_mfma_f32_16x16x32_bf16 v[90:93], v[144:147], v[184:187], v[90:93]
	v_mfma_f32_16x16x32_bf16 v[90:93], v[140:143], v[180:183], v[90:93]
	v_mfma_f32_16x16x32_bf16 v[74:77], v[140:143], v[188:191], v[74:77]
	v_mfma_f32_16x16x32_bf16 v[74:77], v[144:147], v[216:219], v[74:77]
	v_mfma_f32_16x16x32_bf16 v[78:81], v[136:139], v[216:219], v[78:81]
	v_mfma_f32_16x16x32_bf16 v[78:81], v[132:135], v[188:191], v[78:81]
	v_mfma_f32_16x16x32_bf16 v[118:121], v[148:151], v[164:167], v[118:121]
	v_mfma_f32_16x16x32_bf16 v[118:121], v[152:155], v[168:171], v[118:121]
	v_mfma_f32_16x16x32_bf16 v[114:117], v[160:163], v[168:171], v[114:117]
	v_mfma_f32_16x16x32_bf16 v[114:117], v[156:159], v[164:167], v[114:117]
	v_mfma_f32_16x16x32_bf16 v[98:101], v[156:159], v[172:175], v[98:101]
	v_mfma_f32_16x16x32_bf16 v[98:101], v[160:163], v[176:179], v[98:101]
	v_mfma_f32_16x16x32_bf16 v[102:105], v[152:155], v[176:179], v[102:105]
	v_mfma_f32_16x16x32_bf16 v[102:105], v[148:151], v[172:175], v[102:105]
	v_mfma_f32_16x16x32_bf16 v[86:89], v[148:151], v[180:183], v[86:89]
	v_mfma_f32_16x16x32_bf16 v[86:89], v[152:155], v[184:187], v[86:89]
	v_mfma_f32_16x16x32_bf16 v[82:85], v[160:163], v[184:187], v[82:85]
	v_mfma_f32_16x16x32_bf16 v[82:85], v[156:159], v[180:183], v[82:85]
	v_mfma_f32_16x16x32_bf16 v[66:69], v[156:159], v[188:191], v[66:69]
	v_mfma_f32_16x16x32_bf16 v[66:69], v[160:163], v[216:219], v[66:69]
	v_mfma_f32_16x16x32_bf16 v[70:73], v[152:155], v[216:219], v[70:73]
	v_mfma_f32_16x16x32_bf16 v[70:73], v[148:151], v[188:191], v[70:73]
	s_setprio 0
	s_barrier
	ds_read_b128 v[164:167], v197 offset:49152
	ds_read_b128 v[168:171], v197 offset:50176
	ds_read_b128 v[172:175], v197 offset:51200
	ds_read_b128 v[176:179], v197 offset:52224
	ds_read_b128 v[180:183], v197 offset:53248
	ds_read_b128 v[184:187], v197 offset:54272
	ds_read_b128 v[188:191], v197 offset:55296
	ds_read_b128 v[216:219], v197 offset:56320
	s_add_i32 s24, s57, s26
	v_lshl_add_u64 v[192:193], v[192:193], 0, s[94:95]
	s_mov_b32 m0, s24
	s_nop 0
	global_load_lds_dwordx4 v[192:193], off
	v_lshl_add_u64 v[192:193], v[220:221], 0, s[94:95]
	s_add_i32 m0, s24, 0x2000
	s_add_i32 s24, s58, s26
	global_load_lds_dwordx4 v[192:193], off
	v_lshl_add_u64 v[192:193], v[224:225], 0, s[94:95]
	s_mov_b32 m0, s24
	s_nop 0
	global_load_lds_dwordx4 v[192:193], off
	v_lshl_add_u64 v[192:193], v[226:227], 0, s[94:95]
	s_add_i32 m0, s24, 0x2000
	s_nop 0
	global_load_lds_dwordx4 v[192:193], off
	s_waitcnt vmcnt(6)
	s_waitcnt lgkmcnt(0)
	v_mfma_f32_16x16x32_bf16 v[62:65], v[132:135], v[164:167], v[62:65]
	v_mfma_f32_16x16x32_bf16 v[62:65], v[136:139], v[168:171], v[62:65]
	s_barrier
	s_setprio 1
	v_mfma_f32_16x16x32_bf16 v[58:61], v[144:147], v[168:171], v[58:61]
	v_mfma_f32_16x16x32_bf16 v[58:61], v[140:143], v[164:167], v[58:61]
	v_mfma_f32_16x16x32_bf16 v[42:45], v[140:143], v[172:175], v[42:45]
	v_mfma_f32_16x16x32_bf16 v[42:45], v[144:147], v[176:179], v[42:45]
	v_mfma_f32_16x16x32_bf16 v[46:49], v[136:139], v[176:179], v[46:49]
	v_mfma_f32_16x16x32_bf16 v[46:49], v[132:135], v[172:175], v[46:49]
	v_mfma_f32_16x16x32_bf16 v[30:33], v[132:135], v[180:183], v[30:33]
	v_mfma_f32_16x16x32_bf16 v[30:33], v[136:139], v[184:187], v[30:33]
	v_mfma_f32_16x16x32_bf16 v[26:29], v[144:147], v[184:187], v[26:29]
	v_mfma_f32_16x16x32_bf16 v[26:29], v[140:143], v[180:183], v[26:29]
	v_mfma_f32_16x16x32_bf16 v[10:13], v[140:143], v[188:191], v[10:13]
	v_mfma_f32_16x16x32_bf16 v[10:13], v[144:147], v[216:219], v[10:13]
	v_mfma_f32_16x16x32_bf16 v[14:17], v[136:139], v[216:219], v[14:17]
	v_mfma_f32_16x16x32_bf16 v[14:17], v[132:135], v[188:191], v[14:17]
	v_mfma_f32_16x16x32_bf16 v[54:57], v[148:151], v[164:167], v[54:57]
	v_mfma_f32_16x16x32_bf16 v[54:57], v[152:155], v[168:171], v[54:57]
	v_mfma_f32_16x16x32_bf16 v[50:53], v[160:163], v[168:171], v[50:53]
	v_mfma_f32_16x16x32_bf16 v[50:53], v[156:159], v[164:167], v[50:53]
	v_mfma_f32_16x16x32_bf16 v[34:37], v[156:159], v[172:175], v[34:37]
	v_mfma_f32_16x16x32_bf16 v[34:37], v[160:163], v[176:179], v[34:37]
	v_mfma_f32_16x16x32_bf16 v[38:41], v[152:155], v[176:179], v[38:41]
	v_mfma_f32_16x16x32_bf16 v[38:41], v[148:151], v[172:175], v[38:41]
	v_mfma_f32_16x16x32_bf16 v[22:25], v[148:151], v[180:183], v[22:25]
	v_mfma_f32_16x16x32_bf16 v[22:25], v[152:155], v[184:187], v[22:25]
	v_mfma_f32_16x16x32_bf16 v[18:21], v[160:163], v[184:187], v[18:21]
	v_mfma_f32_16x16x32_bf16 v[18:21], v[156:159], v[180:183], v[18:21]
	v_mfma_f32_16x16x32_bf16 v[2:5], v[156:159], v[188:191], v[2:5]
	v_mfma_f32_16x16x32_bf16 v[2:5], v[160:163], v[216:219], v[2:5]
	v_mfma_f32_16x16x32_bf16 v[6:9], v[152:155], v[216:219], v[6:9]
	v_mfma_f32_16x16x32_bf16 v[6:9], v[148:151], v[188:191], v[6:9]
	s_setprio 0
	s_barrier
	s_and_b32 s24, s56, 6
	s_cmp_eq_u32 s24, 0
	s_cselect_b64 s[58:59], -1, 0
	s_cmp_ge_u32 s56, s53
	s_cselect_b64 s[24:25], -1, 0
	s_cmp_lt_u32 s56, s53
	s_cselect_b64 s[60:61], -1, 0
	s_and_b64 s[58:59], s[58:59], s[60:61]
	s_andn2_b64 vcc, exec, s[58:59]
	s_cbranch_vccnz .LBB0_768
	ds_read2_b32 v[132:133], v130 offset1:1
	s_waitcnt lgkmcnt(0)
	v_rcp_f32_e32 v131, v133
	s_nop 0
	v_mul_f32_e32 v132, v132, v131
	v_pk_mul_f32 v[128:129], v[128:129], v[132:133] op_sel_hi:[1,0]
	v_pk_mul_f32 v[126:127], v[126:127], v[132:133] op_sel_hi:[1,0]
	v_pk_mul_f32 v[124:125], v[124:125], v[132:133] op_sel_hi:[1,0]
	v_pk_mul_f32 v[122:123], v[122:123], v[132:133] op_sel_hi:[1,0]
	v_pk_mul_f32 v[120:121], v[120:121], v[132:133] op_sel_hi:[1,0]
	v_pk_mul_f32 v[118:119], v[118:119], v[132:133] op_sel_hi:[1,0]
	v_pk_mul_f32 v[116:117], v[116:117], v[132:133] op_sel_hi:[1,0]
	v_pk_mul_f32 v[114:115], v[114:115], v[132:133] op_sel_hi:[1,0]
	ds_read2_b32 v[132:133], v130 offset0:128 offset1:129
	s_waitcnt lgkmcnt(0)
	v_rcp_f32_e32 v131, v133
	s_nop 0
	v_mul_f32_e32 v132, v132, v131
	v_add_u32_e32 v131, 0x400, v130
	v_pk_mul_f32 v[112:113], v[112:113], v[132:133] op_sel_hi:[1,0]
	v_pk_mul_f32 v[110:111], v[110:111], v[132:133] op_sel_hi:[1,0]
	v_pk_mul_f32 v[108:109], v[108:109], v[132:133] op_sel_hi:[1,0]
	v_pk_mul_f32 v[106:107], v[106:107], v[132:133] op_sel_hi:[1,0]
	v_pk_mul_f32 v[104:105], v[104:105], v[132:133] op_sel_hi:[1,0]
	v_pk_mul_f32 v[102:103], v[102:103], v[132:133] op_sel_hi:[1,0]
	v_pk_mul_f32 v[100:101], v[100:101], v[132:133] op_sel_hi:[1,0]
	v_pk_mul_f32 v[98:99], v[98:99], v[132:133] op_sel_hi:[1,0]
	ds_read2_b32 v[132:133], v131 offset1:1
	s_waitcnt lgkmcnt(0)
	v_rcp_f32_e32 v131, v133
	s_nop 0
	v_mul_f32_e32 v132, v132, v131
	v_add_u32_e32 v131, 0x600, v130
	v_pk_mul_f32 v[96:97], v[96:97], v[132:133] op_sel_hi:[1,0]
	v_pk_mul_f32 v[94:95], v[94:95], v[132:133] op_sel_hi:[1,0]
	v_pk_mul_f32 v[92:93], v[92:93], v[132:133] op_sel_hi:[1,0]
	v_pk_mul_f32 v[90:91], v[90:91], v[132:133] op_sel_hi:[1,0]
	v_pk_mul_f32 v[88:89], v[88:89], v[132:133] op_sel_hi:[1,0]
	v_pk_mul_f32 v[86:87], v[86:87], v[132:133] op_sel_hi:[1,0]
	v_pk_mul_f32 v[84:85], v[84:85], v[132:133] op_sel_hi:[1,0]
	v_pk_mul_f32 v[82:83], v[82:83], v[132:133] op_sel_hi:[1,0]
	ds_read2_b32 v[132:133], v131 offset1:1
	s_waitcnt lgkmcnt(0)
	v_rcp_f32_e32 v131, v133
	s_nop 0
	v_mul_f32_e32 v132, v132, v131
	v_add_u32_e32 v131, 0x1000, v130
	v_pk_mul_f32 v[80:81], v[80:81], v[132:133] op_sel_hi:[1,0]
	v_pk_mul_f32 v[78:79], v[78:79], v[132:133] op_sel_hi:[1,0]
	v_pk_mul_f32 v[76:77], v[76:77], v[132:133] op_sel_hi:[1,0]
	v_pk_mul_f32 v[74:75], v[74:75], v[132:133] op_sel_hi:[1,0]
	v_pk_mul_f32 v[72:73], v[72:73], v[132:133] op_sel_hi:[1,0]
	v_pk_mul_f32 v[70:71], v[70:71], v[132:133] op_sel_hi:[1,0]
	v_pk_mul_f32 v[68:69], v[68:69], v[132:133] op_sel_hi:[1,0]
	v_pk_mul_f32 v[66:67], v[66:67], v[132:133] op_sel_hi:[1,0]
	ds_read2_b32 v[132:133], v131 offset1:1
	s_waitcnt lgkmcnt(0)
	v_rcp_f32_e32 v131, v133
	s_nop 0
	v_mul_f32_e32 v132, v132, v131
	v_add_u32_e32 v131, 0x1200, v130
	v_pk_mul_f32 v[64:65], v[64:65], v[132:133] op_sel_hi:[1,0]
	v_pk_mul_f32 v[62:63], v[62:63], v[132:133] op_sel_hi:[1,0]
	v_pk_mul_f32 v[60:61], v[60:61], v[132:133] op_sel_hi:[1,0]
	v_pk_mul_f32 v[58:59], v[58:59], v[132:133] op_sel_hi:[1,0]
	v_pk_mul_f32 v[56:57], v[56:57], v[132:133] op_sel_hi:[1,0]
	v_pk_mul_f32 v[54:55], v[54:55], v[132:133] op_sel_hi:[1,0]
	v_pk_mul_f32 v[52:53], v[52:53], v[132:133] op_sel_hi:[1,0]
	v_pk_mul_f32 v[50:51], v[50:51], v[132:133] op_sel_hi:[1,0]
	ds_read2_b32 v[132:133], v131 offset1:1
	s_waitcnt lgkmcnt(0)
	v_rcp_f32_e32 v131, v133
	s_nop 0
	v_mul_f32_e32 v132, v132, v131
	v_add_u32_e32 v131, 0x1400, v130
	v_pk_mul_f32 v[48:49], v[48:49], v[132:133] op_sel_hi:[1,0]
	v_pk_mul_f32 v[46:47], v[46:47], v[132:133] op_sel_hi:[1,0]
	v_pk_mul_f32 v[44:45], v[44:45], v[132:133] op_sel_hi:[1,0]
	v_pk_mul_f32 v[42:43], v[42:43], v[132:133] op_sel_hi:[1,0]
	v_pk_mul_f32 v[40:41], v[40:41], v[132:133] op_sel_hi:[1,0]
	v_pk_mul_f32 v[38:39], v[38:39], v[132:133] op_sel_hi:[1,0]
	v_pk_mul_f32 v[36:37], v[36:37], v[132:133] op_sel_hi:[1,0]
	v_pk_mul_f32 v[34:35], v[34:35], v[132:133] op_sel_hi:[1,0]
	ds_read2_b32 v[132:133], v131 offset1:1
	s_waitcnt lgkmcnt(0)
	v_rcp_f32_e32 v131, v133
	s_nop 0
	v_mul_f32_e32 v132, v132, v131
	v_add_u32_e32 v131, 0x1600, v130
	v_pk_mul_f32 v[32:33], v[32:33], v[132:133] op_sel_hi:[1,0]
	v_pk_mul_f32 v[30:31], v[30:31], v[132:133] op_sel_hi:[1,0]
	v_pk_mul_f32 v[28:29], v[28:29], v[132:133] op_sel_hi:[1,0]
	v_pk_mul_f32 v[26:27], v[26:27], v[132:133] op_sel_hi:[1,0]
	v_pk_mul_f32 v[24:25], v[24:25], v[132:133] op_sel_hi:[1,0]
	v_pk_mul_f32 v[22:23], v[22:23], v[132:133] op_sel_hi:[1,0]
	v_pk_mul_f32 v[20:21], v[20:21], v[132:133] op_sel_hi:[1,0]
	v_pk_mul_f32 v[18:19], v[18:19], v[132:133] op_sel_hi:[1,0]
	ds_read2_b32 v[132:133], v131 offset1:1
	s_waitcnt lgkmcnt(0)
	v_rcp_f32_e32 v131, v133
	s_nop 0
	v_mul_f32_e32 v132, v132, v131
	v_pk_mul_f32 v[16:17], v[16:17], v[132:133] op_sel_hi:[1,0]
	v_pk_mul_f32 v[14:15], v[14:15], v[132:133] op_sel_hi:[1,0]
	v_pk_mul_f32 v[12:13], v[12:13], v[132:133] op_sel_hi:[1,0]
	v_pk_mul_f32 v[10:11], v[10:11], v[132:133] op_sel_hi:[1,0]
	v_pk_mul_f32 v[8:9], v[8:9], v[132:133] op_sel_hi:[1,0]
	v_pk_mul_f32 v[6:7], v[6:7], v[132:133] op_sel_hi:[1,0]
	v_pk_mul_f32 v[4:5], v[4:5], v[132:133] op_sel_hi:[1,0]
	v_pk_mul_f32 v[2:3], v[2:3], v[132:133] op_sel_hi:[1,0]
	s_branch .LBB0_768

.Lrealign_5:
.LBB0_850:
	s_sub_u32 vcc_lo, s18, s12
	s_subb_u32 vcc_hi, s19, 0
	s_mov_b32 m0, s33
	s_nop 0
	global_load_lds_dwordx4 v210, vcc
	s_mov_b32 m0, s34
	s_nop 0
	global_load_lds_dwordx4 v212, vcc
	ds_read_b128 v[150:153], v234
	ds_read_b128 v[154:157], v234 offset:1024
	ds_read_b128 v[158:161], v234 offset:2048
	ds_read_b128 v[162:165], v234 offset:3072
	ds_read_b128 v[170:173], v234 offset:4096
	ds_read_b128 v[174:177], v234 offset:5120
	ds_read_b128 v[178:181], v234 offset:6144
	ds_read_b128 v[190:193], v234 offset:7168
	ds_read_b128 v[66:69], v198
	ds_read_b128 v[78:81], v198 offset:1024
	ds_read_b128 v[82:85], v198 offset:2048
	ds_read_b128 v[98:101], v198 offset:3072
	ds_read_b128 v[106:109], v198 offset:16384
	ds_read_b128 v[118:121], v198 offset:17408
	ds_read_b128 v[130:133], v198 offset:18432
	ds_read_b128 v[142:145], v198 offset:19456
	s_add_i32 s55, s20, 2
	s_add_u32 s56, s18, 0x80
	s_addc_u32 s21, s19, 0
	s_add_i32 s58, 0, 0x10000
	s_cmp_eq_u32 s35, s20
	s_cselect_b32 s21, s1, s21
	s_cselect_b32 s20, s0, s56
	s_cselect_b32 s57, s17, s54
	s_cselect_b32 s56, s16, s51
	s_add_i32 s59, 0, 0x14000
	s_add_i32 m0, s26, 0xc000
	s_nop 0
	global_load_lds_dwordx4 v210, s[18:19]
	s_add_i32 m0, s26, 0xe000
	s_nop 0
	global_load_lds_dwordx4 v212, s[18:19]
	s_waitcnt vmcnt(8)
	s_waitcnt lgkmcnt(0)
	v_mfma_f32_16x16x32_bf16 v[186:189], v[66:69], v[150:153], v[186:189]
	v_mfma_f32_16x16x32_bf16 v[186:189], v[78:81], v[154:157], v[186:189]
	s_barrier
	s_setprio 1
	v_mfma_f32_16x16x32_bf16 v[182:185], v[98:101], v[154:157], v[182:185]
	v_mfma_f32_16x16x32_bf16 v[182:185], v[82:85], v[150:153], v[182:185]
	v_mfma_f32_16x16x32_bf16 v[134:137], v[82:85], v[158:161], v[134:137]
	v_mfma_f32_16x16x32_bf16 v[134:137], v[98:101], v[162:165], v[134:137]
	v_mfma_f32_16x16x32_bf16 v[138:141], v[78:81], v[162:165], v[138:141]
	v_mfma_f32_16x16x32_bf16 v[138:141], v[66:69], v[158:161], v[138:141]
	v_mfma_f32_16x16x32_bf16 v[114:117], v[66:69], v[170:173], v[114:117]
	v_mfma_f32_16x16x32_bf16 v[114:117], v[78:81], v[174:177], v[114:117]
	v_mfma_f32_16x16x32_bf16 v[110:113], v[98:101], v[174:177], v[110:113]
	v_mfma_f32_16x16x32_bf16 v[110:113], v[82:85], v[170:173], v[110:113]
	v_mfma_f32_16x16x32_bf16 v[86:89], v[82:85], v[178:181], v[86:89]
	v_mfma_f32_16x16x32_bf16 v[86:89], v[98:101], v[190:193], v[86:89]
	v_mfma_f32_16x16x32_bf16 v[90:93], v[78:81], v[190:193], v[90:93]
	v_mfma_f32_16x16x32_bf16 v[90:93], v[66:69], v[178:181], v[90:93]
	v_mfma_f32_16x16x32_bf16 v[166:169], v[106:109], v[150:153], v[166:169]
	v_mfma_f32_16x16x32_bf16 v[166:169], v[118:121], v[154:157], v[166:169]
	v_mfma_f32_16x16x32_bf16 v[146:149], v[142:145], v[154:157], v[146:149]
	v_mfma_f32_16x16x32_bf16 v[146:149], v[130:133], v[150:153], v[146:149]
	v_mfma_f32_16x16x32_bf16 v[122:125], v[130:133], v[158:161], v[122:125]
	v_mfma_f32_16x16x32_bf16 v[122:125], v[142:145], v[162:165], v[122:125]
	v_mfma_f32_16x16x32_bf16 v[126:129], v[118:121], v[162:165], v[126:129]
	v_mfma_f32_16x16x32_bf16 v[126:129], v[106:109], v[158:161], v[126:129]
	v_mfma_f32_16x16x32_bf16 v[102:105], v[106:109], v[170:173], v[102:105]
	v_mfma_f32_16x16x32_bf16 v[102:105], v[118:121], v[174:177], v[102:105]
	v_mfma_f32_16x16x32_bf16 v[94:97], v[142:145], v[174:177], v[94:97]
	v_mfma_f32_16x16x32_bf16 v[94:97], v[130:133], v[170:173], v[94:97]
	v_mfma_f32_16x16x32_bf16 v[70:73], v[130:133], v[178:181], v[70:73]
	v_mfma_f32_16x16x32_bf16 v[70:73], v[142:145], v[190:193], v[70:73]
	v_mfma_f32_16x16x32_bf16 v[74:77], v[118:121], v[190:193], v[74:77]
	v_mfma_f32_16x16x32_bf16 v[74:77], v[106:109], v[178:181], v[74:77]
	s_setprio 0
	s_barrier
	ds_read_b128 v[150:153], v234 offset:16384
	ds_read_b128 v[154:157], v234 offset:17408
	ds_read_b128 v[158:161], v234 offset:18432
	ds_read_b128 v[162:165], v234 offset:19456
	ds_read_b128 v[170:173], v234 offset:20480
	ds_read_b128 v[174:177], v234 offset:21504
	ds_read_b128 v[178:181], v234 offset:22528
	ds_read_b128 v[190:193], v234 offset:23552
	s_add_i32 s58, s58, s24
	v_lshl_add_u64 v[214:215], s[56:57], 0, v[194:195]
	s_mov_b32 m0, s58
	s_nop 0
	global_load_lds_dwordx4 v194, s[56:57]
	s_add_i32 m0, s58, 0x2000
	v_lshl_add_u64 v[216:217], s[56:57], 0, v[204:205]
	s_add_u32 s56, s56, s12
	s_addc_u32 s57, s57, 0
	s_add_i32 s58, s59, s24
	global_load_lds_dwordx4 v[216:217], off
	v_lshl_add_u64 v[218:219], s[56:57], 0, v[194:195]
	s_mov_b32 m0, s58
	v_lshl_add_u64 v[220:221], s[56:57], 0, v[204:205]
	global_load_lds_dwordx4 v194, s[56:57]
	s_add_i32 m0, s58, 0x2000
	s_nop 0
	global_load_lds_dwordx4 v204, s[56:57]
	s_waitcnt vmcnt(6)
	s_waitcnt lgkmcnt(0)
	v_mfma_f32_16x16x32_bf16 v[62:65], v[66:69], v[150:153], v[62:65]
	v_mfma_f32_16x16x32_bf16 v[62:65], v[78:81], v[154:157], v[62:65]
	s_barrier
	s_setprio 1
	v_mfma_f32_16x16x32_bf16 v[58:61], v[98:101], v[154:157], v[58:61]
	v_mfma_f32_16x16x32_bf16 v[58:61], v[82:85], v[150:153], v[58:61]
	v_mfma_f32_16x16x32_bf16 v[42:45], v[82:85], v[158:161], v[42:45]
	v_mfma_f32_16x16x32_bf16 v[42:45], v[98:101], v[162:165], v[42:45]
	v_mfma_f32_16x16x32_bf16 v[46:49], v[78:81], v[162:165], v[46:49]
	v_mfma_f32_16x16x32_bf16 v[46:49], v[66:69], v[158:161], v[46:49]
	v_mfma_f32_16x16x32_bf16 v[30:33], v[66:69], v[170:173], v[30:33]
	v_mfma_f32_16x16x32_bf16 v[30:33], v[78:81], v[174:177], v[30:33]
	v_mfma_f32_16x16x32_bf16 v[26:29], v[98:101], v[174:177], v[26:29]
	v_mfma_f32_16x16x32_bf16 v[26:29], v[82:85], v[170:173], v[26:29]
	v_mfma_f32_16x16x32_bf16 v[10:13], v[82:85], v[178:181], v[10:13]
	v_mfma_f32_16x16x32_bf16 v[10:13], v[98:101], v[190:193], v[10:13]
	v_mfma_f32_16x16x32_bf16 v[14:17], v[78:81], v[190:193], v[14:17]
	v_mfma_f32_16x16x32_bf16 v[14:17], v[66:69], v[178:181], v[14:17]
	v_mfma_f32_16x16x32_bf16 v[54:57], v[106:109], v[150:153], v[54:57]
	v_mfma_f32_16x16x32_bf16 v[54:57], v[118:121], v[154:157], v[54:57]
	v_mfma_f32_16x16x32_bf16 v[50:53], v[142:145], v[154:157], v[50:53]
	v_mfma_f32_16x16x32_bf16 v[50:53], v[130:133], v[150:153], v[50:53]
	v_mfma_f32_16x16x32_bf16 v[34:37], v[130:133], v[158:161], v[34:37]
	v_mfma_f32_16x16x32_bf16 v[34:37], v[142:145], v[162:165], v[34:37]
	v_mfma_f32_16x16x32_bf16 v[38:41], v[118:121], v[162:165], v[38:41]
	v_mfma_f32_16x16x32_bf16 v[38:41], v[106:109], v[158:161], v[38:41]
	v_mfma_f32_16x16x32_bf16 v[22:25], v[106:109], v[170:173], v[22:25]
	v_mfma_f32_16x16x32_bf16 v[22:25], v[118:121], v[174:177], v[22:25]
	v_mfma_f32_16x16x32_bf16 v[18:21], v[142:145], v[174:177], v[18:21]
	v_mfma_f32_16x16x32_bf16 v[18:21], v[130:133], v[170:173], v[18:21]
	v_mfma_f32_16x16x32_bf16 v[2:5], v[130:133], v[178:181], v[2:5]
	v_mfma_f32_16x16x32_bf16 v[2:5], v[142:145], v[190:193], v[2:5]
	v_mfma_f32_16x16x32_bf16 v[6:9], v[118:121], v[190:193], v[6:9]
	v_mfma_f32_16x16x32_bf16 v[6:9], v[106:109], v[178:181], v[6:9]
	s_setprio 0
	s_barrier
	s_mov_b32 m0, s26
	s_nop 0
	global_load_lds_dwordx4 v208, s[20:21]
	s_mov_b32 m0, s27
	s_nop 0
	global_load_lds_dwordx4 v206, s[20:21]
	ds_read_b128 v[150:153], v234 offset:32768
	ds_read_b128 v[154:157], v234 offset:33792
	ds_read_b128 v[158:161], v234 offset:34816
	ds_read_b128 v[162:165], v234 offset:35840
	ds_read_b128 v[170:173], v234 offset:36864
	ds_read_b128 v[174:177], v234 offset:37888
	ds_read_b128 v[178:181], v234 offset:38912
	ds_read_b128 v[190:193], v234 offset:39936
	ds_read_b128 v[66:69], v198 offset:32768
	ds_read_b128 v[78:81], v198 offset:33792
	ds_read_b128 v[82:85], v198 offset:34816
	ds_read_b128 v[98:101], v198 offset:35840
	ds_read_b128 v[106:109], v198 offset:49152
	ds_read_b128 v[118:121], v198 offset:50176
	ds_read_b128 v[130:133], v198 offset:51200
	ds_read_b128 v[142:145], v198 offset:52224
	s_add_i32 s56, 0, 0x18000
	s_add_i32 s57, 0, 0x1c000
	s_add_u32 s20, s20, s12
	s_addc_u32 s21, s21, 0
	s_mov_b32 m0, s28
	s_nop 0
	global_load_lds_dwordx4 v208, s[20:21]
	s_mov_b32 m0, s29
	s_nop 0
	global_load_lds_dwordx4 v206, s[20:21]
	s_waitcnt vmcnt(8)
	s_waitcnt lgkmcnt(0)
	v_mfma_f32_16x16x32_bf16 v[186:189], v[66:69], v[150:153], v[186:189]
	v_mfma_f32_16x16x32_bf16 v[186:189], v[78:81], v[154:157], v[186:189]
	s_barrier
	s_setprio 1
	v_mfma_f32_16x16x32_bf16 v[182:185], v[98:101], v[154:157], v[182:185]
	v_mfma_f32_16x16x32_bf16 v[182:185], v[82:85], v[150:153], v[182:185]
	v_mfma_f32_16x16x32_bf16 v[134:137], v[82:85], v[158:161], v[134:137]
	v_mfma_f32_16x16x32_bf16 v[134:137], v[98:101], v[162:165], v[134:137]
	v_mfma_f32_16x16x32_bf16 v[138:141], v[78:81], v[162:165], v[138:141]
	v_mfma_f32_16x16x32_bf16 v[138:141], v[66:69], v[158:161], v[138:141]
	v_mfma_f32_16x16x32_bf16 v[114:117], v[66:69], v[170:173], v[114:117]
	v_mfma_f32_16x16x32_bf16 v[114:117], v[78:81], v[174:177], v[114:117]
	v_mfma_f32_16x16x32_bf16 v[110:113], v[98:101], v[174:177], v[110:113]
	v_mfma_f32_16x16x32_bf16 v[110:113], v[82:85], v[170:173], v[110:113]
	v_mfma_f32_16x16x32_bf16 v[86:89], v[82:85], v[178:181], v[86:89]
	v_mfma_f32_16x16x32_bf16 v[86:89], v[98:101], v[190:193], v[86:89]
	v_mfma_f32_16x16x32_bf16 v[90:93], v[78:81], v[190:193], v[90:93]
	v_mfma_f32_16x16x32_bf16 v[90:93], v[66:69], v[178:181], v[90:93]
	v_mfma_f32_16x16x32_bf16 v[166:169], v[106:109], v[150:153], v[166:169]
	v_mfma_f32_16x16x32_bf16 v[166:169], v[118:121], v[154:157], v[166:169]
	v_mfma_f32_16x16x32_bf16 v[146:149], v[142:145], v[154:157], v[146:149]
	v_mfma_f32_16x16x32_bf16 v[146:149], v[130:133], v[150:153], v[146:149]
	v_mfma_f32_16x16x32_bf16 v[122:125], v[130:133], v[158:161], v[122:125]
	v_mfma_f32_16x16x32_bf16 v[122:125], v[142:145], v[162:165], v[122:125]
	v_mfma_f32_16x16x32_bf16 v[126:129], v[118:121], v[162:165], v[126:129]
	v_mfma_f32_16x16x32_bf16 v[126:129], v[106:109], v[158:161], v[126:129]
	v_mfma_f32_16x16x32_bf16 v[102:105], v[106:109], v[170:173], v[102:105]
	v_mfma_f32_16x16x32_bf16 v[102:105], v[118:121], v[174:177], v[102:105]
	v_mfma_f32_16x16x32_bf16 v[94:97], v[142:145], v[174:177], v[94:97]
	v_mfma_f32_16x16x32_bf16 v[94:97], v[130:133], v[170:173], v[94:97]
	v_mfma_f32_16x16x32_bf16 v[70:73], v[130:133], v[178:181], v[70:73]
	v_mfma_f32_16x16x32_bf16 v[70:73], v[142:145], v[190:193], v[70:73]
	v_mfma_f32_16x16x32_bf16 v[74:77], v[118:121], v[190:193], v[74:77]
	v_mfma_f32_16x16x32_bf16 v[74:77], v[106:109], v[178:181], v[74:77]
	s_setprio 0
	s_barrier
	ds_read_b128 v[150:153], v234 offset:49152
	ds_read_b128 v[154:157], v234 offset:50176
	ds_read_b128 v[158:161], v234 offset:51200
	ds_read_b128 v[162:165], v234 offset:52224
	ds_read_b128 v[170:173], v234 offset:53248
	ds_read_b128 v[174:177], v234 offset:54272
	ds_read_b128 v[178:181], v234 offset:55296
	ds_read_b128 v[190:193], v234 offset:56320
	s_add_i32 s20, s56, s24
	v_lshl_add_u64 v[214:215], v[214:215], 0, s[94:95]
	s_mov_b32 m0, s20
	s_nop 0
	global_load_lds_dwordx4 v[214:215], off
	v_lshl_add_u64 v[214:215], v[216:217], 0, s[94:95]
	s_add_i32 m0, s20, 0x2000
	s_add_i32 s20, s57, s24
	global_load_lds_dwordx4 v[214:215], off
	v_lshl_add_u64 v[214:215], v[218:219], 0, s[94:95]
	s_mov_b32 m0, s20
	s_nop 0
	global_load_lds_dwordx4 v[214:215], off
	v_lshl_add_u64 v[214:215], v[220:221], 0, s[94:95]
	s_add_i32 m0, s20, 0x2000
	s_nop 0
	global_load_lds_dwordx4 v[214:215], off
	s_waitcnt vmcnt(6)
	s_waitcnt lgkmcnt(0)
	v_mfma_f32_16x16x32_bf16 v[62:65], v[66:69], v[150:153], v[62:65]
	v_mfma_f32_16x16x32_bf16 v[62:65], v[78:81], v[154:157], v[62:65]
	s_barrier
	s_setprio 1
	v_mfma_f32_16x16x32_bf16 v[58:61], v[98:101], v[154:157], v[58:61]
	v_mfma_f32_16x16x32_bf16 v[58:61], v[82:85], v[150:153], v[58:61]
	v_mfma_f32_16x16x32_bf16 v[42:45], v[82:85], v[158:161], v[42:45]
	v_mfma_f32_16x16x32_bf16 v[42:45], v[98:101], v[162:165], v[42:45]
	v_mfma_f32_16x16x32_bf16 v[46:49], v[78:81], v[162:165], v[46:49]
	v_mfma_f32_16x16x32_bf16 v[46:49], v[66:69], v[158:161], v[46:49]
	v_mfma_f32_16x16x32_bf16 v[30:33], v[66:69], v[170:173], v[30:33]
	v_mfma_f32_16x16x32_bf16 v[30:33], v[78:81], v[174:177], v[30:33]
	v_mfma_f32_16x16x32_bf16 v[26:29], v[98:101], v[174:177], v[26:29]
	v_mfma_f32_16x16x32_bf16 v[26:29], v[82:85], v[170:173], v[26:29]
	v_mfma_f32_16x16x32_bf16 v[10:13], v[82:85], v[178:181], v[10:13]
	v_mfma_f32_16x16x32_bf16 v[10:13], v[98:101], v[190:193], v[10:13]
	s_add_u32 s18, s18, 0x100
	v_mfma_f32_16x16x32_bf16 v[14:17], v[78:81], v[190:193], v[14:17]
	v_mfma_f32_16x16x32_bf16 v[14:17], v[66:69], v[178:181], v[14:17]
	s_addc_u32 s19, s19, 0
	v_mfma_f32_16x16x32_bf16 v[54:57], v[106:109], v[150:153], v[54:57]
	v_mfma_f32_16x16x32_bf16 v[54:57], v[118:121], v[154:157], v[54:57]
	s_add_u32 s51, s51, 0x100
	v_mfma_f32_16x16x32_bf16 v[50:53], v[142:145], v[154:157], v[50:53]
	v_mfma_f32_16x16x32_bf16 v[50:53], v[130:133], v[150:153], v[50:53]
	s_addc_u32 s54, s54, 0
	v_mfma_f32_16x16x32_bf16 v[34:37], v[130:133], v[158:161], v[34:37]
	v_mfma_f32_16x16x32_bf16 v[34:37], v[142:145], v[162:165], v[34:37]
	s_cmp_ge_u32 s55, s53
	v_mfma_f32_16x16x32_bf16 v[38:41], v[118:121], v[162:165], v[38:41]
	v_mfma_f32_16x16x32_bf16 v[38:41], v[106:109], v[158:161], v[38:41]
	s_mov_b32 s20, s55
	v_mfma_f32_16x16x32_bf16 v[22:25], v[106:109], v[170:173], v[22:25]
	v_mfma_f32_16x16x32_bf16 v[22:25], v[118:121], v[174:177], v[22:25]
	v_mfma_f32_16x16x32_bf16 v[18:21], v[142:145], v[174:177], v[18:21]
	v_mfma_f32_16x16x32_bf16 v[18:21], v[130:133], v[170:173], v[18:21]
	v_mfma_f32_16x16x32_bf16 v[2:5], v[130:133], v[178:181], v[2:5]
	v_mfma_f32_16x16x32_bf16 v[2:5], v[142:145], v[190:193], v[2:5]
	v_mfma_f32_16x16x32_bf16 v[6:9], v[118:121], v[190:193], v[6:9]
	v_mfma_f32_16x16x32_bf16 v[6:9], v[106:109], v[178:181], v[6:9]
	s_setprio 0
	s_barrier
	s_cbranch_scc0 .LBB0_850

.Lrealign_6:
.LBB0_875:
	s_sub_u32 vcc_lo, s20, s12
	s_subb_u32 vcc_hi, s21, 0
	s_mov_b32 m0, s51
	s_nop 0
	global_load_lds_dwordx4 v210, vcc
	s_mov_b32 m0, s53
	s_nop 0
	global_load_lds_dwordx4 v212, vcc
	ds_read_b128 v[162:165], v237
	ds_read_b128 v[166:169], v237 offset:1024
	ds_read_b128 v[170:173], v237 offset:2048
	ds_read_b128 v[174:177], v237 offset:3072
	ds_read_b128 v[178:181], v237 offset:4096
	ds_read_b128 v[182:185], v237 offset:5120
	ds_read_b128 v[186:189], v237 offset:6144
	ds_read_b128 v[190:193], v237 offset:7168
	ds_read_b128 v[130:133], v235
	ds_read_b128 v[134:137], v235 offset:1024
	ds_read_b128 v[138:141], v235 offset:2048
	ds_read_b128 v[142:145], v235 offset:3072
	ds_read_b128 v[146:149], v235 offset:16384
	ds_read_b128 v[150:153], v235 offset:17408
	ds_read_b128 v[154:157], v235 offset:18432
	ds_read_b128 v[158:161], v235 offset:19456
	s_add_i32 s29, s26, 2
	s_add_u32 s62, s20, 0x80
	s_addc_u32 s27, s21, 0
	s_add_i32 s64, 0, 0x10000
	s_cmp_eq_u32 s17, s26
	s_cselect_b32 s27, s7, s27
	s_cselect_b32 s26, s6, s62
	s_cselect_b32 s63, s19, s28
	s_cselect_b32 s62, s18, s23
	s_add_i32 s65, 0, 0x14000
	s_add_i32 m0, s37, 0xc000
	s_nop 0
	global_load_lds_dwordx4 v210, s[20:21]
	s_add_i32 m0, s37, 0xe000
	s_nop 0
	global_load_lds_dwordx4 v212, s[20:21]
	s_waitcnt vmcnt(8)
	s_waitcnt lgkmcnt(0)
	v_mfma_f32_16x16x32_bf16 v[126:129], v[130:133], v[162:165], v[126:129]
	v_mfma_f32_16x16x32_bf16 v[126:129], v[134:137], v[166:169], v[126:129]
	s_barrier
	s_setprio 1
	v_mfma_f32_16x16x32_bf16 v[122:125], v[142:145], v[166:169], v[122:125]
	v_mfma_f32_16x16x32_bf16 v[122:125], v[138:141], v[162:165], v[122:125]
	v_mfma_f32_16x16x32_bf16 v[106:109], v[138:141], v[170:173], v[106:109]
	v_mfma_f32_16x16x32_bf16 v[106:109], v[142:145], v[174:177], v[106:109]
	v_mfma_f32_16x16x32_bf16 v[110:113], v[134:137], v[174:177], v[110:113]
	v_mfma_f32_16x16x32_bf16 v[110:113], v[130:133], v[170:173], v[110:113]
	v_mfma_f32_16x16x32_bf16 v[94:97], v[130:133], v[178:181], v[94:97]
	v_mfma_f32_16x16x32_bf16 v[94:97], v[134:137], v[182:185], v[94:97]
	v_mfma_f32_16x16x32_bf16 v[90:93], v[142:145], v[182:185], v[90:93]
	v_mfma_f32_16x16x32_bf16 v[90:93], v[138:141], v[178:181], v[90:93]
	v_mfma_f32_16x16x32_bf16 v[74:77], v[138:141], v[186:189], v[74:77]
	v_mfma_f32_16x16x32_bf16 v[74:77], v[142:145], v[190:193], v[74:77]
	v_mfma_f32_16x16x32_bf16 v[78:81], v[134:137], v[190:193], v[78:81]
	v_mfma_f32_16x16x32_bf16 v[78:81], v[130:133], v[186:189], v[78:81]
	v_mfma_f32_16x16x32_bf16 v[118:121], v[146:149], v[162:165], v[118:121]
	v_mfma_f32_16x16x32_bf16 v[118:121], v[150:153], v[166:169], v[118:121]
	v_mfma_f32_16x16x32_bf16 v[114:117], v[158:161], v[166:169], v[114:117]
	v_mfma_f32_16x16x32_bf16 v[114:117], v[154:157], v[162:165], v[114:117]
	v_mfma_f32_16x16x32_bf16 v[98:101], v[154:157], v[170:173], v[98:101]
	v_mfma_f32_16x16x32_bf16 v[98:101], v[158:161], v[174:177], v[98:101]
	v_mfma_f32_16x16x32_bf16 v[102:105], v[150:153], v[174:177], v[102:105]
	v_mfma_f32_16x16x32_bf16 v[102:105], v[146:149], v[170:173], v[102:105]
	v_mfma_f32_16x16x32_bf16 v[86:89], v[146:149], v[178:181], v[86:89]
	v_mfma_f32_16x16x32_bf16 v[86:89], v[150:153], v[182:185], v[86:89]
	v_mfma_f32_16x16x32_bf16 v[82:85], v[158:161], v[182:185], v[82:85]
	v_mfma_f32_16x16x32_bf16 v[82:85], v[154:157], v[178:181], v[82:85]
	v_mfma_f32_16x16x32_bf16 v[66:69], v[154:157], v[186:189], v[66:69]
	v_mfma_f32_16x16x32_bf16 v[66:69], v[158:161], v[190:193], v[66:69]
	v_mfma_f32_16x16x32_bf16 v[70:73], v[150:153], v[190:193], v[70:73]
	v_mfma_f32_16x16x32_bf16 v[70:73], v[146:149], v[186:189], v[70:73]
	s_setprio 0
	s_barrier
	ds_read_b128 v[162:165], v237 offset:16384
	ds_read_b128 v[166:169], v237 offset:17408
	ds_read_b128 v[170:173], v237 offset:18432
	ds_read_b128 v[174:177], v237 offset:19456
	ds_read_b128 v[178:181], v237 offset:20480
	ds_read_b128 v[182:185], v237 offset:21504
	ds_read_b128 v[186:189], v237 offset:22528
	ds_read_b128 v[190:193], v237 offset:23552
	s_add_i32 s64, s64, s36
	v_lshl_add_u64 v[198:199], s[62:63], 0, v[194:195]
	s_mov_b32 m0, s64
	s_nop 0
	global_load_lds_dwordx4 v194, s[62:63]
	s_add_i32 m0, s64, 0x2000
	v_lshl_add_u64 v[214:215], s[62:63], 0, v[208:209]
	s_add_u32 s62, s62, s12
	s_addc_u32 s63, s63, 0
	s_add_i32 s64, s65, s36
	global_load_lds_dwordx4 v[214:215], off
	v_lshl_add_u64 v[216:217], s[62:63], 0, v[194:195]
	s_mov_b32 m0, s64
	v_lshl_add_u64 v[218:219], s[62:63], 0, v[208:209]
	global_load_lds_dwordx4 v194, s[62:63]
	s_add_i32 m0, s64, 0x2000
	s_nop 0
	global_load_lds_dwordx4 v208, s[62:63]
	s_waitcnt vmcnt(6)
	s_waitcnt lgkmcnt(0)
	v_mfma_f32_16x16x32_bf16 v[62:65], v[130:133], v[162:165], v[62:65]
	v_mfma_f32_16x16x32_bf16 v[62:65], v[134:137], v[166:169], v[62:65]
	s_barrier
	s_setprio 1
	v_mfma_f32_16x16x32_bf16 v[58:61], v[142:145], v[166:169], v[58:61]
	v_mfma_f32_16x16x32_bf16 v[58:61], v[138:141], v[162:165], v[58:61]
	v_mfma_f32_16x16x32_bf16 v[42:45], v[138:141], v[170:173], v[42:45]
	v_mfma_f32_16x16x32_bf16 v[42:45], v[142:145], v[174:177], v[42:45]
	v_mfma_f32_16x16x32_bf16 v[46:49], v[134:137], v[174:177], v[46:49]
	v_mfma_f32_16x16x32_bf16 v[46:49], v[130:133], v[170:173], v[46:49]
	v_mfma_f32_16x16x32_bf16 v[30:33], v[130:133], v[178:181], v[30:33]
	v_mfma_f32_16x16x32_bf16 v[30:33], v[134:137], v[182:185], v[30:33]
	v_mfma_f32_16x16x32_bf16 v[26:29], v[142:145], v[182:185], v[26:29]
	v_mfma_f32_16x16x32_bf16 v[26:29], v[138:141], v[178:181], v[26:29]
	v_mfma_f32_16x16x32_bf16 v[10:13], v[138:141], v[186:189], v[10:13]
	v_mfma_f32_16x16x32_bf16 v[10:13], v[142:145], v[190:193], v[10:13]
	v_mfma_f32_16x16x32_bf16 v[14:17], v[134:137], v[190:193], v[14:17]
	v_mfma_f32_16x16x32_bf16 v[14:17], v[130:133], v[186:189], v[14:17]
	v_mfma_f32_16x16x32_bf16 v[54:57], v[146:149], v[162:165], v[54:57]
	v_mfma_f32_16x16x32_bf16 v[54:57], v[150:153], v[166:169], v[54:57]
	v_mfma_f32_16x16x32_bf16 v[50:53], v[158:161], v[166:169], v[50:53]
	v_mfma_f32_16x16x32_bf16 v[50:53], v[154:157], v[162:165], v[50:53]
	v_mfma_f32_16x16x32_bf16 v[34:37], v[154:157], v[170:173], v[34:37]
	v_mfma_f32_16x16x32_bf16 v[34:37], v[158:161], v[174:177], v[34:37]
	v_mfma_f32_16x16x32_bf16 v[38:41], v[150:153], v[174:177], v[38:41]
	v_mfma_f32_16x16x32_bf16 v[38:41], v[146:149], v[170:173], v[38:41]
	v_mfma_f32_16x16x32_bf16 v[22:25], v[146:149], v[178:181], v[22:25]
	v_mfma_f32_16x16x32_bf16 v[22:25], v[150:153], v[182:185], v[22:25]
	v_mfma_f32_16x16x32_bf16 v[18:21], v[158:161], v[182:185], v[18:21]
	v_mfma_f32_16x16x32_bf16 v[18:21], v[154:157], v[178:181], v[18:21]
	v_mfma_f32_16x16x32_bf16 v[2:5], v[154:157], v[186:189], v[2:5]
	v_mfma_f32_16x16x32_bf16 v[2:5], v[158:161], v[190:193], v[2:5]
	v_mfma_f32_16x16x32_bf16 v[6:9], v[150:153], v[190:193], v[6:9]
	v_mfma_f32_16x16x32_bf16 v[6:9], v[146:149], v[186:189], v[6:9]
	s_setprio 0
	s_barrier
	s_mov_b32 m0, s37
	s_nop 0
	global_load_lds_dwordx4 v204, s[26:27]
	s_mov_b32 m0, s38
	s_nop 0
	global_load_lds_dwordx4 v206, s[26:27]
	ds_read_b128 v[162:165], v237 offset:32768
	ds_read_b128 v[166:169], v237 offset:33792
	ds_read_b128 v[170:173], v237 offset:34816
	ds_read_b128 v[174:177], v237 offset:35840
	ds_read_b128 v[178:181], v237 offset:36864
	ds_read_b128 v[182:185], v237 offset:37888
	ds_read_b128 v[186:189], v237 offset:38912
	ds_read_b128 v[190:193], v237 offset:39936
	ds_read_b128 v[130:133], v235 offset:32768
	ds_read_b128 v[134:137], v235 offset:33792
	ds_read_b128 v[138:141], v235 offset:34816
	ds_read_b128 v[142:145], v235 offset:35840
	ds_read_b128 v[146:149], v235 offset:49152
	ds_read_b128 v[150:153], v235 offset:50176
	ds_read_b128 v[154:157], v235 offset:51200
	ds_read_b128 v[158:161], v235 offset:52224
	s_add_i32 s62, 0, 0x18000
	s_add_i32 s63, 0, 0x1c000
	s_add_u32 s26, s26, s12
	s_addc_u32 s27, s27, 0
	s_mov_b32 m0, s39
	s_nop 0
	global_load_lds_dwordx4 v204, s[26:27]
	s_mov_b32 m0, s50
	s_nop 0
	global_load_lds_dwordx4 v206, s[26:27]
	s_waitcnt vmcnt(8)
	s_waitcnt lgkmcnt(0)
	v_mfma_f32_16x16x32_bf16 v[126:129], v[130:133], v[162:165], v[126:129]
	v_mfma_f32_16x16x32_bf16 v[126:129], v[134:137], v[166:169], v[126:129]
	s_barrier
	s_setprio 1
	v_mfma_f32_16x16x32_bf16 v[122:125], v[142:145], v[166:169], v[122:125]
	v_mfma_f32_16x16x32_bf16 v[122:125], v[138:141], v[162:165], v[122:125]
	v_mfma_f32_16x16x32_bf16 v[106:109], v[138:141], v[170:173], v[106:109]
	v_mfma_f32_16x16x32_bf16 v[106:109], v[142:145], v[174:177], v[106:109]
	v_mfma_f32_16x16x32_bf16 v[110:113], v[134:137], v[174:177], v[110:113]
	v_mfma_f32_16x16x32_bf16 v[110:113], v[130:133], v[170:173], v[110:113]
	v_mfma_f32_16x16x32_bf16 v[94:97], v[130:133], v[178:181], v[94:97]
	v_mfma_f32_16x16x32_bf16 v[94:97], v[134:137], v[182:185], v[94:97]
	v_mfma_f32_16x16x32_bf16 v[90:93], v[142:145], v[182:185], v[90:93]
	v_mfma_f32_16x16x32_bf16 v[90:93], v[138:141], v[178:181], v[90:93]
	v_mfma_f32_16x16x32_bf16 v[74:77], v[138:141], v[186:189], v[74:77]
	v_mfma_f32_16x16x32_bf16 v[74:77], v[142:145], v[190:193], v[74:77]
	v_mfma_f32_16x16x32_bf16 v[78:81], v[134:137], v[190:193], v[78:81]
	v_mfma_f32_16x16x32_bf16 v[78:81], v[130:133], v[186:189], v[78:81]
	v_mfma_f32_16x16x32_bf16 v[118:121], v[146:149], v[162:165], v[118:121]
	v_mfma_f32_16x16x32_bf16 v[118:121], v[150:153], v[166:169], v[118:121]
	v_mfma_f32_16x16x32_bf16 v[114:117], v[158:161], v[166:169], v[114:117]
	v_mfma_f32_16x16x32_bf16 v[114:117], v[154:157], v[162:165], v[114:117]
	v_mfma_f32_16x16x32_bf16 v[98:101], v[154:157], v[170:173], v[98:101]
	v_mfma_f32_16x16x32_bf16 v[98:101], v[158:161], v[174:177], v[98:101]
	v_mfma_f32_16x16x32_bf16 v[102:105], v[150:153], v[174:177], v[102:105]
	v_mfma_f32_16x16x32_bf16 v[102:105], v[146:149], v[170:173], v[102:105]
	v_mfma_f32_16x16x32_bf16 v[86:89], v[146:149], v[178:181], v[86:89]
	v_mfma_f32_16x16x32_bf16 v[86:89], v[150:153], v[182:185], v[86:89]
	v_mfma_f32_16x16x32_bf16 v[82:85], v[158:161], v[182:185], v[82:85]
	v_mfma_f32_16x16x32_bf16 v[82:85], v[154:157], v[178:181], v[82:85]
	v_mfma_f32_16x16x32_bf16 v[66:69], v[154:157], v[186:189], v[66:69]
	v_mfma_f32_16x16x32_bf16 v[66:69], v[158:161], v[190:193], v[66:69]
	v_mfma_f32_16x16x32_bf16 v[70:73], v[150:153], v[190:193], v[70:73]
	v_mfma_f32_16x16x32_bf16 v[70:73], v[146:149], v[186:189], v[70:73]
	s_setprio 0
	s_barrier
	ds_read_b128 v[162:165], v237 offset:49152
	ds_read_b128 v[166:169], v237 offset:50176
	ds_read_b128 v[170:173], v237 offset:51200
	ds_read_b128 v[174:177], v237 offset:52224
	ds_read_b128 v[178:181], v237 offset:53248
	ds_read_b128 v[182:185], v237 offset:54272
	ds_read_b128 v[186:189], v237 offset:55296
	ds_read_b128 v[190:193], v237 offset:56320
	s_add_i32 s26, s62, s36
	v_lshl_add_u64 v[198:199], v[198:199], 0, s[94:95]
	s_mov_b32 m0, s26
	s_nop 0
	global_load_lds_dwordx4 v[198:199], off
	v_lshl_add_u64 v[198:199], v[214:215], 0, s[94:95]
	s_add_i32 m0, s26, 0x2000
	s_add_i32 s26, s63, s36
	global_load_lds_dwordx4 v[198:199], off
	v_lshl_add_u64 v[198:199], v[216:217], 0, s[94:95]
	s_mov_b32 m0, s26
	s_nop 0
	global_load_lds_dwordx4 v[198:199], off
	v_lshl_add_u64 v[198:199], v[218:219], 0, s[94:95]
	s_add_i32 m0, s26, 0x2000
	s_nop 0
	global_load_lds_dwordx4 v[198:199], off
	s_waitcnt vmcnt(6)
	s_waitcnt lgkmcnt(0)
	v_mfma_f32_16x16x32_bf16 v[62:65], v[130:133], v[162:165], v[62:65]
	v_mfma_f32_16x16x32_bf16 v[62:65], v[134:137], v[166:169], v[62:65]
	s_barrier
	s_setprio 1
	v_mfma_f32_16x16x32_bf16 v[58:61], v[142:145], v[166:169], v[58:61]
	v_mfma_f32_16x16x32_bf16 v[58:61], v[138:141], v[162:165], v[58:61]
	v_mfma_f32_16x16x32_bf16 v[42:45], v[138:141], v[170:173], v[42:45]
	v_mfma_f32_16x16x32_bf16 v[42:45], v[142:145], v[174:177], v[42:45]
	v_mfma_f32_16x16x32_bf16 v[46:49], v[134:137], v[174:177], v[46:49]
	v_mfma_f32_16x16x32_bf16 v[46:49], v[130:133], v[170:173], v[46:49]
	v_mfma_f32_16x16x32_bf16 v[30:33], v[130:133], v[178:181], v[30:33]
	v_mfma_f32_16x16x32_bf16 v[30:33], v[134:137], v[182:185], v[30:33]
	v_mfma_f32_16x16x32_bf16 v[26:29], v[142:145], v[182:185], v[26:29]
	v_mfma_f32_16x16x32_bf16 v[26:29], v[138:141], v[178:181], v[26:29]
	v_mfma_f32_16x16x32_bf16 v[10:13], v[138:141], v[186:189], v[10:13]
	v_mfma_f32_16x16x32_bf16 v[10:13], v[142:145], v[190:193], v[10:13]
	s_add_u32 s20, s20, 0x100
	v_mfma_f32_16x16x32_bf16 v[14:17], v[134:137], v[190:193], v[14:17]
	v_mfma_f32_16x16x32_bf16 v[14:17], v[130:133], v[186:189], v[14:17]
	s_addc_u32 s21, s21, 0
	v_mfma_f32_16x16x32_bf16 v[54:57], v[146:149], v[162:165], v[54:57]
	v_mfma_f32_16x16x32_bf16 v[54:57], v[150:153], v[166:169], v[54:57]
	s_add_u32 s23, s23, 0x100
	v_mfma_f32_16x16x32_bf16 v[50:53], v[158:161], v[166:169], v[50:53]
	v_mfma_f32_16x16x32_bf16 v[50:53], v[154:157], v[162:165], v[50:53]
	s_addc_u32 s28, s28, 0
	v_mfma_f32_16x16x32_bf16 v[34:37], v[154:157], v[170:173], v[34:37]
	v_mfma_f32_16x16x32_bf16 v[34:37], v[158:161], v[174:177], v[34:37]
	s_cmp_ge_i32 s29, s25
	v_mfma_f32_16x16x32_bf16 v[38:41], v[150:153], v[174:177], v[38:41]
	v_mfma_f32_16x16x32_bf16 v[38:41], v[146:149], v[170:173], v[38:41]
	s_mov_b32 s26, s29
	v_mfma_f32_16x16x32_bf16 v[22:25], v[146:149], v[178:181], v[22:25]
	v_mfma_f32_16x16x32_bf16 v[22:25], v[150:153], v[182:185], v[22:25]
	v_mfma_f32_16x16x32_bf16 v[18:21], v[158:161], v[182:185], v[18:21]
	v_mfma_f32_16x16x32_bf16 v[18:21], v[154:157], v[178:181], v[18:21]
	v_mfma_f32_16x16x32_bf16 v[2:5], v[154:157], v[186:189], v[2:5]
	v_mfma_f32_16x16x32_bf16 v[2:5], v[158:161], v[190:193], v[2:5]
	v_mfma_f32_16x16x32_bf16 v[6:9], v[150:153], v[190:193], v[6:9]
	v_mfma_f32_16x16x32_bf16 v[6:9], v[146:149], v[186:189], v[6:9]
	s_setprio 0
	s_barrier
	s_cbranch_scc0 .LBB0_875
	v_readlane_b32 s64, v254, 51
	v_readlane_b32 s65, v254, 52
	s_branch .LBB0_878

.Lrealign_7:
.LBB0_973:
	s_add_u32 vcc_lo, s0, 0xffffc000
	s_addc_u32 vcc_hi, s1, -1
	s_mov_b32 m0, s59
	s_nop 0
	global_load_lds_dwordx4 v146, vcc
	s_mov_b32 m0, s60
	s_nop 0
	global_load_lds_dwordx4 v148, vcc
	ds_read_b128 v[174:177], v247
	ds_read_b128 v[178:181], v247 offset:1024
	ds_read_b128 v[182:185], v247 offset:2048
	ds_read_b128 v[186:189], v247 offset:3072
	ds_read_b128 v[190:193], v247 offset:4096
	ds_read_b128 v[204:207], v247 offset:5120
	ds_read_b128 v[208:211], v247 offset:6144
	ds_read_b128 v[212:215], v247 offset:7168
	ds_read_b128 v[130:133], v246
	ds_read_b128 v[134:137], v246 offset:1024
	ds_read_b128 v[150:153], v246 offset:2048
	ds_read_b128 v[154:157], v246 offset:3072
	ds_read_b128 v[158:161], v246 offset:16384
	ds_read_b128 v[162:165], v246 offset:17408
	ds_read_b128 v[166:169], v246 offset:18432
	ds_read_b128 v[170:173], v246 offset:19456
	s_add_u32 s4, s0, 0x100
	s_addc_u32 s5, s1, 0
	s_add_i32 s40, 0, 0x10000
	s_cmp_eq_u32 s39, 28
	s_cselect_b32 s11, s35, s5
	s_cselect_b32 s10, s34, s4
	s_cselect_b32 s7, s13, s38
	s_cselect_b32 s6, s29, s33
	s_add_i32 s41, 0, 0x14000
	s_add_i32 m0, s49, 0xc000
	s_nop 0
	global_load_lds_dwordx4 v146, s[0:1]
	s_add_i32 m0, s49, 0xe000
	s_nop 0
	global_load_lds_dwordx4 v148, s[0:1]
	s_waitcnt vmcnt(8)
	s_waitcnt lgkmcnt(0)
	v_mfma_f32_16x16x32_bf16 v[126:129], v[130:133], v[174:177], v[126:129]
	v_mfma_f32_16x16x32_bf16 v[126:129], v[134:137], v[178:181], v[126:129]
	s_barrier
	s_setprio 1
	v_mfma_f32_16x16x32_bf16 v[62:65], v[154:157], v[178:181], v[62:65]
	v_mfma_f32_16x16x32_bf16 v[62:65], v[150:153], v[174:177], v[62:65]
	v_mfma_f32_16x16x32_bf16 v[58:61], v[150:153], v[182:185], v[58:61]
	v_mfma_f32_16x16x32_bf16 v[58:61], v[154:157], v[186:189], v[58:61]
	v_mfma_f32_16x16x32_bf16 v[122:125], v[134:137], v[186:189], v[122:125]
	v_mfma_f32_16x16x32_bf16 v[122:125], v[130:133], v[182:185], v[122:125]
	v_mfma_f32_16x16x32_bf16 v[114:117], v[130:133], v[190:193], v[114:117]
	v_mfma_f32_16x16x32_bf16 v[114:117], v[134:137], v[204:207], v[114:117]
	v_mfma_f32_16x16x32_bf16 v[50:53], v[154:157], v[204:207], v[50:53]
	v_mfma_f32_16x16x32_bf16 v[50:53], v[150:153], v[190:193], v[50:53]
	v_mfma_f32_16x16x32_bf16 v[42:45], v[150:153], v[208:211], v[42:45]
	v_mfma_f32_16x16x32_bf16 v[42:45], v[154:157], v[212:215], v[42:45]
	v_mfma_f32_16x16x32_bf16 v[106:109], v[134:137], v[212:215], v[106:109]
	v_mfma_f32_16x16x32_bf16 v[106:109], v[130:133], v[208:211], v[106:109]
	v_mfma_f32_16x16x32_bf16 v[118:121], v[158:161], v[174:177], v[118:121]
	v_mfma_f32_16x16x32_bf16 v[118:121], v[162:165], v[178:181], v[118:121]
	v_mfma_f32_16x16x32_bf16 v[54:57], v[170:173], v[178:181], v[54:57]
	v_mfma_f32_16x16x32_bf16 v[54:57], v[166:169], v[174:177], v[54:57]
	v_mfma_f32_16x16x32_bf16 v[46:49], v[166:169], v[182:185], v[46:49]
	v_mfma_f32_16x16x32_bf16 v[46:49], v[170:173], v[186:189], v[46:49]
	v_mfma_f32_16x16x32_bf16 v[110:113], v[162:165], v[186:189], v[110:113]
	v_mfma_f32_16x16x32_bf16 v[110:113], v[158:161], v[182:185], v[110:113]
	v_mfma_f32_16x16x32_bf16 v[102:105], v[158:161], v[190:193], v[102:105]
	v_mfma_f32_16x16x32_bf16 v[102:105], v[162:165], v[204:207], v[102:105]
	v_mfma_f32_16x16x32_bf16 v[38:41], v[170:173], v[204:207], v[38:41]
	v_mfma_f32_16x16x32_bf16 v[38:41], v[166:169], v[190:193], v[38:41]
	v_mfma_f32_16x16x32_bf16 v[34:37], v[166:169], v[208:211], v[34:37]
	v_mfma_f32_16x16x32_bf16 v[34:37], v[170:173], v[212:215], v[34:37]
	v_mfma_f32_16x16x32_bf16 v[98:101], v[162:165], v[212:215], v[98:101]
	v_mfma_f32_16x16x32_bf16 v[98:101], v[158:161], v[208:211], v[98:101]
	s_setprio 0
	s_barrier
	ds_read_b128 v[174:177], v247 offset:16384
	ds_read_b128 v[178:181], v247 offset:17408
	ds_read_b128 v[182:185], v247 offset:18432
	ds_read_b128 v[186:189], v247 offset:19456
	ds_read_b128 v[190:193], v247 offset:20480
	ds_read_b128 v[204:207], v247 offset:21504
	ds_read_b128 v[208:211], v247 offset:22528
	ds_read_b128 v[212:215], v247 offset:23552
	s_add_i32 s0, s40, s48
	s_mov_b32 m0, s0
	s_nop 0
	global_load_lds_dwordx4 v140, s[6:7]
	s_add_i32 m0, s0, 0x2000
	s_add_u32 s0, s6, 0x80000
	s_addc_u32 s1, s7, 0
	s_add_i32 s40, s41, s48
	global_load_lds_dwordx4 v144, s[6:7]
	s_mov_b32 m0, s40
	s_nop 0
	global_load_lds_dwordx4 v140, s[0:1]
	s_add_i32 m0, s40, 0x2000
	s_nop 0
	global_load_lds_dwordx4 v144, s[0:1]
	s_waitcnt vmcnt(6)
	s_waitcnt lgkmcnt(0)
	v_mfma_f32_16x16x32_bf16 v[94:97], v[130:133], v[174:177], v[94:97]
	v_mfma_f32_16x16x32_bf16 v[94:97], v[134:137], v[178:181], v[94:97]
	s_barrier
	s_setprio 1
	v_mfma_f32_16x16x32_bf16 v[30:33], v[154:157], v[178:181], v[30:33]
	v_mfma_f32_16x16x32_bf16 v[30:33], v[150:153], v[174:177], v[30:33]
	v_mfma_f32_16x16x32_bf16 v[26:29], v[150:153], v[182:185], v[26:29]
	v_mfma_f32_16x16x32_bf16 v[26:29], v[154:157], v[186:189], v[26:29]
	v_mfma_f32_16x16x32_bf16 v[90:93], v[134:137], v[186:189], v[90:93]
	v_mfma_f32_16x16x32_bf16 v[90:93], v[130:133], v[182:185], v[90:93]
	v_mfma_f32_16x16x32_bf16 v[82:85], v[130:133], v[190:193], v[82:85]
	v_mfma_f32_16x16x32_bf16 v[82:85], v[134:137], v[204:207], v[82:85]
	v_mfma_f32_16x16x32_bf16 v[18:21], v[154:157], v[204:207], v[18:21]
	v_mfma_f32_16x16x32_bf16 v[18:21], v[150:153], v[190:193], v[18:21]
	v_mfma_f32_16x16x32_bf16 v[10:13], v[150:153], v[208:211], v[10:13]
	v_mfma_f32_16x16x32_bf16 v[10:13], v[154:157], v[212:215], v[10:13]
	v_mfma_f32_16x16x32_bf16 v[74:77], v[134:137], v[212:215], v[74:77]
	v_mfma_f32_16x16x32_bf16 v[74:77], v[130:133], v[208:211], v[74:77]
	v_mfma_f32_16x16x32_bf16 v[86:89], v[158:161], v[174:177], v[86:89]
	v_mfma_f32_16x16x32_bf16 v[86:89], v[162:165], v[178:181], v[86:89]
	v_mfma_f32_16x16x32_bf16 v[22:25], v[170:173], v[178:181], v[22:25]
	v_mfma_f32_16x16x32_bf16 v[22:25], v[166:169], v[174:177], v[22:25]
	v_mfma_f32_16x16x32_bf16 v[14:17], v[166:169], v[182:185], v[14:17]
	v_mfma_f32_16x16x32_bf16 v[14:17], v[170:173], v[186:189], v[14:17]
	v_mfma_f32_16x16x32_bf16 v[78:81], v[162:165], v[186:189], v[78:81]
	v_mfma_f32_16x16x32_bf16 v[78:81], v[158:161], v[182:185], v[78:81]
	v_mfma_f32_16x16x32_bf16 v[70:73], v[158:161], v[190:193], v[70:73]
	v_mfma_f32_16x16x32_bf16 v[70:73], v[162:165], v[204:207], v[70:73]
	v_mfma_f32_16x16x32_bf16 v[6:9], v[170:173], v[204:207], v[6:9]
	v_mfma_f32_16x16x32_bf16 v[6:9], v[166:169], v[190:193], v[6:9]
	v_mfma_f32_16x16x32_bf16 v[2:5], v[166:169], v[208:211], v[2:5]
	v_mfma_f32_16x16x32_bf16 v[2:5], v[170:173], v[212:215], v[2:5]
	v_mfma_f32_16x16x32_bf16 v[66:69], v[162:165], v[212:215], v[66:69]
	v_mfma_f32_16x16x32_bf16 v[66:69], v[158:161], v[208:211], v[66:69]
	s_setprio 0
	s_barrier
	s_mov_b32 m0, s49
	s_nop 0
	global_load_lds_dwordx4 v138, s[10:11]
	s_mov_b32 m0, s70
	s_nop 0
	global_load_lds_dwordx4 v142, s[10:11]
	ds_read_b128 v[174:177], v247 offset:32768
	ds_read_b128 v[178:181], v247 offset:33792
	ds_read_b128 v[182:185], v247 offset:34816
	ds_read_b128 v[186:189], v247 offset:35840
	ds_read_b128 v[190:193], v247 offset:36864
	ds_read_b128 v[204:207], v247 offset:37888
	ds_read_b128 v[208:211], v247 offset:38912
	ds_read_b128 v[212:215], v247 offset:39936
	ds_read_b128 v[130:133], v246 offset:32768
	ds_read_b128 v[134:137], v246 offset:33792
	ds_read_b128 v[150:153], v246 offset:34816
	ds_read_b128 v[154:157], v246 offset:35840
	ds_read_b128 v[158:161], v246 offset:49152
	ds_read_b128 v[162:165], v246 offset:50176
	ds_read_b128 v[166:169], v246 offset:51200
	ds_read_b128 v[170:173], v246 offset:52224
	s_add_i32 s40, 0, 0x18000
	s_add_i32 s41, 0, 0x1c000
	s_add_u32 s0, s10, 0x4000
	s_addc_u32 s1, s11, 0
	s_mov_b32 m0, s71
	s_nop 0
	global_load_lds_dwordx4 v138, s[0:1]
	s_mov_b32 m0, s73
	s_nop 0
	global_load_lds_dwordx4 v142, s[0:1]
	s_waitcnt vmcnt(8)
	s_waitcnt lgkmcnt(0)
	v_mfma_f32_16x16x32_bf16 v[126:129], v[130:133], v[174:177], v[126:129]
	v_mfma_f32_16x16x32_bf16 v[126:129], v[134:137], v[178:181], v[126:129]
	s_barrier
	s_setprio 1
	v_mfma_f32_16x16x32_bf16 v[62:65], v[154:157], v[178:181], v[62:65]
	v_mfma_f32_16x16x32_bf16 v[62:65], v[150:153], v[174:177], v[62:65]
	v_mfma_f32_16x16x32_bf16 v[58:61], v[150:153], v[182:185], v[58:61]
	v_mfma_f32_16x16x32_bf16 v[58:61], v[154:157], v[186:189], v[58:61]
	v_mfma_f32_16x16x32_bf16 v[122:125], v[134:137], v[186:189], v[122:125]
	v_mfma_f32_16x16x32_bf16 v[122:125], v[130:133], v[182:185], v[122:125]
	v_mfma_f32_16x16x32_bf16 v[114:117], v[130:133], v[190:193], v[114:117]
	v_mfma_f32_16x16x32_bf16 v[114:117], v[134:137], v[204:207], v[114:117]
	v_mfma_f32_16x16x32_bf16 v[50:53], v[154:157], v[204:207], v[50:53]
	v_mfma_f32_16x16x32_bf16 v[50:53], v[150:153], v[190:193], v[50:53]
	v_mfma_f32_16x16x32_bf16 v[42:45], v[150:153], v[208:211], v[42:45]
	v_mfma_f32_16x16x32_bf16 v[42:45], v[154:157], v[212:215], v[42:45]
	v_mfma_f32_16x16x32_bf16 v[106:109], v[134:137], v[212:215], v[106:109]
	v_mfma_f32_16x16x32_bf16 v[106:109], v[130:133], v[208:211], v[106:109]
	v_mfma_f32_16x16x32_bf16 v[118:121], v[158:161], v[174:177], v[118:121]
	v_mfma_f32_16x16x32_bf16 v[118:121], v[162:165], v[178:181], v[118:121]
	v_mfma_f32_16x16x32_bf16 v[54:57], v[170:173], v[178:181], v[54:57]
	v_mfma_f32_16x16x32_bf16 v[54:57], v[166:169], v[174:177], v[54:57]
	v_mfma_f32_16x16x32_bf16 v[46:49], v[166:169], v[182:185], v[46:49]
	v_mfma_f32_16x16x32_bf16 v[46:49], v[170:173], v[186:189], v[46:49]
	v_mfma_f32_16x16x32_bf16 v[110:113], v[162:165], v[186:189], v[110:113]
	v_mfma_f32_16x16x32_bf16 v[110:113], v[158:161], v[182:185], v[110:113]
	v_mfma_f32_16x16x32_bf16 v[102:105], v[158:161], v[190:193], v[102:105]
	v_mfma_f32_16x16x32_bf16 v[102:105], v[162:165], v[204:207], v[102:105]
	v_mfma_f32_16x16x32_bf16 v[38:41], v[170:173], v[204:207], v[38:41]
	v_mfma_f32_16x16x32_bf16 v[38:41], v[166:169], v[190:193], v[38:41]
	v_mfma_f32_16x16x32_bf16 v[34:37], v[166:169], v[208:211], v[34:37]
	v_mfma_f32_16x16x32_bf16 v[34:37], v[170:173], v[212:215], v[34:37]
	v_mfma_f32_16x16x32_bf16 v[98:101], v[162:165], v[212:215], v[98:101]
	v_mfma_f32_16x16x32_bf16 v[98:101], v[158:161], v[208:211], v[98:101]
	s_setprio 0
	s_barrier
	ds_read_b128 v[174:177], v247 offset:49152
	ds_read_b128 v[178:181], v247 offset:50176
	ds_read_b128 v[182:185], v247 offset:51200
	ds_read_b128 v[186:189], v247 offset:52224
	ds_read_b128 v[190:193], v247 offset:53248
	ds_read_b128 v[204:207], v247 offset:54272
	ds_read_b128 v[208:211], v247 offset:55296
	ds_read_b128 v[212:215], v247 offset:56320
	s_add_i32 s0, s40, s48
	s_add_u32 vcc_lo, s6, s94
	s_addc_u32 vcc_hi, s7, s95
	s_mov_b32 m0, s0
	s_nop 0
	global_load_lds_dwordx4 v140, vcc
	s_add_i32 m0, s0, 0x2000
	s_add_u32 s0, s6, 0x80080
	s_addc_u32 s1, s7, 0
	s_add_i32 s6, s41, s48
	global_load_lds_dwordx4 v144, vcc
	s_mov_b32 m0, s6
	s_nop 0
	global_load_lds_dwordx4 v140, s[0:1]
	s_add_i32 m0, s6, 0x2000
	s_nop 0
	global_load_lds_dwordx4 v144, s[0:1]
	s_waitcnt vmcnt(6)
	s_waitcnt lgkmcnt(0)
	v_mfma_f32_16x16x32_bf16 v[94:97], v[130:133], v[174:177], v[94:97]
	v_mfma_f32_16x16x32_bf16 v[94:97], v[134:137], v[178:181], v[94:97]
	s_barrier
	s_setprio 1
	v_mfma_f32_16x16x32_bf16 v[30:33], v[154:157], v[178:181], v[30:33]
	v_mfma_f32_16x16x32_bf16 v[30:33], v[150:153], v[174:177], v[30:33]
	v_mfma_f32_16x16x32_bf16 v[26:29], v[150:153], v[182:185], v[26:29]
	v_mfma_f32_16x16x32_bf16 v[26:29], v[154:157], v[186:189], v[26:29]
	v_mfma_f32_16x16x32_bf16 v[90:93], v[134:137], v[186:189], v[90:93]
	v_mfma_f32_16x16x32_bf16 v[90:93], v[130:133], v[182:185], v[90:93]
	v_mfma_f32_16x16x32_bf16 v[82:85], v[130:133], v[190:193], v[82:85]
	v_mfma_f32_16x16x32_bf16 v[82:85], v[134:137], v[204:207], v[82:85]
	v_mfma_f32_16x16x32_bf16 v[18:21], v[154:157], v[204:207], v[18:21]
	v_mfma_f32_16x16x32_bf16 v[18:21], v[150:153], v[190:193], v[18:21]
	v_mfma_f32_16x16x32_bf16 v[10:13], v[150:153], v[208:211], v[10:13]
	v_mfma_f32_16x16x32_bf16 v[10:13], v[154:157], v[212:215], v[10:13]
	s_add_i32 s39, s39, 2
	v_mfma_f32_16x16x32_bf16 v[74:77], v[134:137], v[212:215], v[74:77]
	v_mfma_f32_16x16x32_bf16 v[74:77], v[130:133], v[208:211], v[74:77]
	s_add_u32 s33, s33, 0x100
	v_mfma_f32_16x16x32_bf16 v[86:89], v[158:161], v[174:177], v[86:89]
	v_mfma_f32_16x16x32_bf16 v[86:89], v[162:165], v[178:181], v[86:89]
	s_addc_u32 s38, s38, 0
	v_mfma_f32_16x16x32_bf16 v[22:25], v[170:173], v[178:181], v[22:25]
	v_mfma_f32_16x16x32_bf16 v[22:25], v[166:169], v[174:177], v[22:25]
	s_cmp_gt_u32 s39, 29
	v_mfma_f32_16x16x32_bf16 v[14:17], v[166:169], v[182:185], v[14:17]
	v_mfma_f32_16x16x32_bf16 v[14:17], v[170:173], v[186:189], v[14:17]
	s_mov_b64 s[0:1], s[4:5]
	v_mfma_f32_16x16x32_bf16 v[78:81], v[162:165], v[186:189], v[78:81]
	v_mfma_f32_16x16x32_bf16 v[78:81], v[158:161], v[182:185], v[78:81]
	v_mfma_f32_16x16x32_bf16 v[70:73], v[158:161], v[190:193], v[70:73]
	v_mfma_f32_16x16x32_bf16 v[70:73], v[162:165], v[204:207], v[70:73]
	v_mfma_f32_16x16x32_bf16 v[6:9], v[170:173], v[204:207], v[6:9]
	v_mfma_f32_16x16x32_bf16 v[6:9], v[166:169], v[190:193], v[6:9]
	v_mfma_f32_16x16x32_bf16 v[2:5], v[166:169], v[208:211], v[2:5]
	v_mfma_f32_16x16x32_bf16 v[2:5], v[170:173], v[212:215], v[2:5]
	v_mfma_f32_16x16x32_bf16 v[66:69], v[162:165], v[212:215], v[66:69]
	v_mfma_f32_16x16x32_bf16 v[66:69], v[158:161], v[208:211], v[66:69]
	s_setprio 0
	s_barrier
	s_cbranch_scc0 .LBB0_973

.Lrealign_8:
.LBB0_1441:
	s_add_u32 vcc_lo, s18, 0xffea0000
	s_addc_u32 vcc_hi, s19, -1
	s_mov_b32 m0, s38
	s_nop 0
	global_load_lds_dwordx4 v210, vcc
	s_mov_b32 m0, s40
	s_nop 0
	global_load_lds_dwordx4 v212, vcc
	ds_read_b128 v[150:153], v234
	ds_read_b128 v[154:157], v234 offset:1024
	ds_read_b128 v[158:161], v234 offset:2048
	ds_read_b128 v[162:165], v234 offset:3072
	ds_read_b128 v[170:173], v234 offset:4096
	ds_read_b128 v[174:177], v234 offset:5120
	ds_read_b128 v[178:181], v234 offset:6144
	ds_read_b128 v[190:193], v234 offset:7168
	ds_read_b128 v[66:69], v198
	ds_read_b128 v[78:81], v198 offset:1024
	ds_read_b128 v[86:89], v198 offset:2048
	ds_read_b128 v[98:101], v198 offset:3072
	ds_read_b128 v[106:109], v198 offset:16384
	ds_read_b128 v[118:121], v198 offset:17408
	ds_read_b128 v[130:133], v198 offset:18432
	ds_read_b128 v[142:145], v198 offset:19456
	s_add_u32 s20, s18, 0x100
	s_addc_u32 s21, s19, 0
	s_add_i32 s49, 0, 0x10000
	s_cmpk_eq_i32 s48, 0x54
	s_cselect_b32 s25, s1, s21
	s_cselect_b32 s24, s0, s20
	s_cselect_b32 s23, s17, s47
	s_cselect_b32 s22, s16, s46
	s_add_i32 s50, 0, 0x14000
	s_add_i32 m0, s28, 0xc000
	s_nop 0
	global_load_lds_dwordx4 v210, s[18:19]
	s_add_i32 m0, s28, 0xe000
	s_nop 0
	global_load_lds_dwordx4 v212, s[18:19]
	s_waitcnt vmcnt(8)
	s_waitcnt lgkmcnt(0)
	v_mfma_f32_16x16x32_bf16 v[186:189], v[66:69], v[150:153], v[186:189]
	v_mfma_f32_16x16x32_bf16 v[186:189], v[78:81], v[154:157], v[186:189]
	s_barrier
	s_setprio 1
	v_mfma_f32_16x16x32_bf16 v[182:185], v[98:101], v[154:157], v[182:185]
	v_mfma_f32_16x16x32_bf16 v[182:185], v[86:89], v[150:153], v[182:185]
	v_mfma_f32_16x16x32_bf16 v[134:137], v[86:89], v[158:161], v[134:137]
	v_mfma_f32_16x16x32_bf16 v[134:137], v[98:101], v[162:165], v[134:137]
	v_mfma_f32_16x16x32_bf16 v[138:141], v[78:81], v[162:165], v[138:141]
	v_mfma_f32_16x16x32_bf16 v[138:141], v[66:69], v[158:161], v[138:141]
	v_mfma_f32_16x16x32_bf16 v[114:117], v[66:69], v[170:173], v[114:117]
	v_mfma_f32_16x16x32_bf16 v[114:117], v[78:81], v[174:177], v[114:117]
	v_mfma_f32_16x16x32_bf16 v[110:113], v[98:101], v[174:177], v[110:113]
	v_mfma_f32_16x16x32_bf16 v[110:113], v[86:89], v[170:173], v[110:113]
	v_mfma_f32_16x16x32_bf16 v[82:85], v[86:89], v[178:181], v[82:85]
	v_mfma_f32_16x16x32_bf16 v[82:85], v[98:101], v[190:193], v[82:85]
	v_mfma_f32_16x16x32_bf16 v[90:93], v[78:81], v[190:193], v[90:93]
	v_mfma_f32_16x16x32_bf16 v[90:93], v[66:69], v[178:181], v[90:93]
	v_mfma_f32_16x16x32_bf16 v[166:169], v[106:109], v[150:153], v[166:169]
	v_mfma_f32_16x16x32_bf16 v[166:169], v[118:121], v[154:157], v[166:169]
	v_mfma_f32_16x16x32_bf16 v[146:149], v[142:145], v[154:157], v[146:149]
	v_mfma_f32_16x16x32_bf16 v[146:149], v[130:133], v[150:153], v[146:149]
	v_mfma_f32_16x16x32_bf16 v[122:125], v[130:133], v[158:161], v[122:125]
	v_mfma_f32_16x16x32_bf16 v[122:125], v[142:145], v[162:165], v[122:125]
	v_mfma_f32_16x16x32_bf16 v[126:129], v[118:121], v[162:165], v[126:129]
	v_mfma_f32_16x16x32_bf16 v[126:129], v[106:109], v[158:161], v[126:129]
	v_mfma_f32_16x16x32_bf16 v[102:105], v[106:109], v[170:173], v[102:105]
	v_mfma_f32_16x16x32_bf16 v[102:105], v[118:121], v[174:177], v[102:105]
	v_mfma_f32_16x16x32_bf16 v[94:97], v[142:145], v[174:177], v[94:97]
	v_mfma_f32_16x16x32_bf16 v[94:97], v[130:133], v[170:173], v[94:97]
	v_mfma_f32_16x16x32_bf16 v[70:73], v[130:133], v[178:181], v[70:73]
	v_mfma_f32_16x16x32_bf16 v[70:73], v[142:145], v[190:193], v[70:73]
	v_mfma_f32_16x16x32_bf16 v[74:77], v[118:121], v[190:193], v[74:77]
	v_mfma_f32_16x16x32_bf16 v[74:77], v[106:109], v[178:181], v[74:77]
	s_setprio 0
	s_barrier
	ds_read_b128 v[150:153], v234 offset:16384
	ds_read_b128 v[154:157], v234 offset:17408
	ds_read_b128 v[158:161], v234 offset:18432
	ds_read_b128 v[162:165], v234 offset:19456
	ds_read_b128 v[170:173], v234 offset:20480
	ds_read_b128 v[174:177], v234 offset:21504
	ds_read_b128 v[178:181], v234 offset:22528
	ds_read_b128 v[190:193], v234 offset:23552
	s_add_i32 s18, s49, s26
	s_mov_b32 m0, s18
	s_nop 0
	global_load_lds_dwordx4 v194, s[22:23]
	s_add_i32 m0, s18, 0x2000
	s_add_u32 s18, s22, 0x160000
	s_addc_u32 s19, s23, 0
	s_add_i32 s49, s50, s26
	global_load_lds_dwordx4 v204, s[22:23]
	s_mov_b32 m0, s49
	s_nop 0
	global_load_lds_dwordx4 v194, s[18:19]
	s_add_i32 m0, s49, 0x2000
	s_nop 0
	global_load_lds_dwordx4 v204, s[18:19]
	s_waitcnt vmcnt(6)
	s_waitcnt lgkmcnt(0)
	v_mfma_f32_16x16x32_bf16 v[62:65], v[66:69], v[150:153], v[62:65]
	v_mfma_f32_16x16x32_bf16 v[62:65], v[78:81], v[154:157], v[62:65]
	s_barrier
	s_setprio 1
	v_mfma_f32_16x16x32_bf16 v[58:61], v[98:101], v[154:157], v[58:61]
	v_mfma_f32_16x16x32_bf16 v[58:61], v[86:89], v[150:153], v[58:61]
	v_mfma_f32_16x16x32_bf16 v[42:45], v[86:89], v[158:161], v[42:45]
	v_mfma_f32_16x16x32_bf16 v[42:45], v[98:101], v[162:165], v[42:45]
	v_mfma_f32_16x16x32_bf16 v[46:49], v[78:81], v[162:165], v[46:49]
	v_mfma_f32_16x16x32_bf16 v[46:49], v[66:69], v[158:161], v[46:49]
	v_mfma_f32_16x16x32_bf16 v[30:33], v[66:69], v[170:173], v[30:33]
	v_mfma_f32_16x16x32_bf16 v[30:33], v[78:81], v[174:177], v[30:33]
	v_mfma_f32_16x16x32_bf16 v[26:29], v[98:101], v[174:177], v[26:29]
	v_mfma_f32_16x16x32_bf16 v[26:29], v[86:89], v[170:173], v[26:29]
	v_mfma_f32_16x16x32_bf16 v[10:13], v[86:89], v[178:181], v[10:13]
	v_mfma_f32_16x16x32_bf16 v[10:13], v[98:101], v[190:193], v[10:13]
	v_mfma_f32_16x16x32_bf16 v[14:17], v[78:81], v[190:193], v[14:17]
	v_mfma_f32_16x16x32_bf16 v[14:17], v[66:69], v[178:181], v[14:17]
	v_mfma_f32_16x16x32_bf16 v[54:57], v[106:109], v[150:153], v[54:57]
	v_mfma_f32_16x16x32_bf16 v[54:57], v[118:121], v[154:157], v[54:57]
	v_mfma_f32_16x16x32_bf16 v[50:53], v[142:145], v[154:157], v[50:53]
	v_mfma_f32_16x16x32_bf16 v[50:53], v[130:133], v[150:153], v[50:53]
	v_mfma_f32_16x16x32_bf16 v[34:37], v[130:133], v[158:161], v[34:37]
	v_mfma_f32_16x16x32_bf16 v[34:37], v[142:145], v[162:165], v[34:37]
	v_mfma_f32_16x16x32_bf16 v[38:41], v[118:121], v[162:165], v[38:41]
	v_mfma_f32_16x16x32_bf16 v[38:41], v[106:109], v[158:161], v[38:41]
	v_mfma_f32_16x16x32_bf16 v[22:25], v[106:109], v[170:173], v[22:25]
	v_mfma_f32_16x16x32_bf16 v[22:25], v[118:121], v[174:177], v[22:25]
	v_mfma_f32_16x16x32_bf16 v[18:21], v[142:145], v[174:177], v[18:21]
	v_mfma_f32_16x16x32_bf16 v[18:21], v[130:133], v[170:173], v[18:21]
	v_mfma_f32_16x16x32_bf16 v[2:5], v[130:133], v[178:181], v[2:5]
	v_mfma_f32_16x16x32_bf16 v[2:5], v[142:145], v[190:193], v[2:5]
	v_mfma_f32_16x16x32_bf16 v[6:9], v[118:121], v[190:193], v[6:9]
	v_mfma_f32_16x16x32_bf16 v[6:9], v[106:109], v[178:181], v[6:9]
	s_setprio 0
	s_barrier
	s_mov_b32 m0, s28
	s_nop 0
	global_load_lds_dwordx4 v208, s[24:25]
	s_mov_b32 m0, s29
	s_nop 0
	global_load_lds_dwordx4 v206, s[24:25]
	ds_read_b128 v[150:153], v234 offset:32768
	ds_read_b128 v[154:157], v234 offset:33792
	ds_read_b128 v[158:161], v234 offset:34816
	ds_read_b128 v[162:165], v234 offset:35840
	ds_read_b128 v[170:173], v234 offset:36864
	ds_read_b128 v[174:177], v234 offset:37888
	ds_read_b128 v[178:181], v234 offset:38912
	ds_read_b128 v[190:193], v234 offset:39936
	ds_read_b128 v[66:69], v198 offset:32768
	ds_read_b128 v[78:81], v198 offset:33792
	ds_read_b128 v[86:89], v198 offset:34816
	ds_read_b128 v[98:101], v198 offset:35840
	ds_read_b128 v[106:109], v198 offset:49152
	ds_read_b128 v[118:121], v198 offset:50176
	ds_read_b128 v[130:133], v198 offset:51200
	ds_read_b128 v[142:145], v198 offset:52224
	s_add_i32 s49, 0, 0x18000
	s_add_i32 s50, 0, 0x1c000
	s_add_u32 s18, s24, 0x160000
	s_addc_u32 s19, s25, 0
	s_mov_b32 m0, s33
	s_nop 0
	global_load_lds_dwordx4 v208, s[18:19]
	s_mov_b32 m0, s37
	s_nop 0
	global_load_lds_dwordx4 v206, s[18:19]
	s_waitcnt vmcnt(8)
	s_waitcnt lgkmcnt(0)
	v_mfma_f32_16x16x32_bf16 v[186:189], v[66:69], v[150:153], v[186:189]
	v_mfma_f32_16x16x32_bf16 v[186:189], v[78:81], v[154:157], v[186:189]
	s_barrier
	s_setprio 1
	v_mfma_f32_16x16x32_bf16 v[182:185], v[98:101], v[154:157], v[182:185]
	v_mfma_f32_16x16x32_bf16 v[182:185], v[86:89], v[150:153], v[182:185]
	v_mfma_f32_16x16x32_bf16 v[134:137], v[86:89], v[158:161], v[134:137]
	v_mfma_f32_16x16x32_bf16 v[134:137], v[98:101], v[162:165], v[134:137]
	v_mfma_f32_16x16x32_bf16 v[138:141], v[78:81], v[162:165], v[138:141]
	v_mfma_f32_16x16x32_bf16 v[138:141], v[66:69], v[158:161], v[138:141]
	v_mfma_f32_16x16x32_bf16 v[114:117], v[66:69], v[170:173], v[114:117]
	v_mfma_f32_16x16x32_bf16 v[114:117], v[78:81], v[174:177], v[114:117]
	v_mfma_f32_16x16x32_bf16 v[110:113], v[98:101], v[174:177], v[110:113]
	v_mfma_f32_16x16x32_bf16 v[110:113], v[86:89], v[170:173], v[110:113]
	v_mfma_f32_16x16x32_bf16 v[82:85], v[86:89], v[178:181], v[82:85]
	v_mfma_f32_16x16x32_bf16 v[82:85], v[98:101], v[190:193], v[82:85]
	v_mfma_f32_16x16x32_bf16 v[90:93], v[78:81], v[190:193], v[90:93]
	v_mfma_f32_16x16x32_bf16 v[90:93], v[66:69], v[178:181], v[90:93]
	v_mfma_f32_16x16x32_bf16 v[166:169], v[106:109], v[150:153], v[166:169]
	v_mfma_f32_16x16x32_bf16 v[166:169], v[118:121], v[154:157], v[166:169]
	v_mfma_f32_16x16x32_bf16 v[146:149], v[142:145], v[154:157], v[146:149]
	v_mfma_f32_16x16x32_bf16 v[146:149], v[130:133], v[150:153], v[146:149]
	v_mfma_f32_16x16x32_bf16 v[122:125], v[130:133], v[158:161], v[122:125]
	v_mfma_f32_16x16x32_bf16 v[122:125], v[142:145], v[162:165], v[122:125]
	v_mfma_f32_16x16x32_bf16 v[126:129], v[118:121], v[162:165], v[126:129]
	v_mfma_f32_16x16x32_bf16 v[126:129], v[106:109], v[158:161], v[126:129]
	v_mfma_f32_16x16x32_bf16 v[102:105], v[106:109], v[170:173], v[102:105]
	v_mfma_f32_16x16x32_bf16 v[102:105], v[118:121], v[174:177], v[102:105]
	v_mfma_f32_16x16x32_bf16 v[94:97], v[142:145], v[174:177], v[94:97]
	v_mfma_f32_16x16x32_bf16 v[94:97], v[130:133], v[170:173], v[94:97]
	v_mfma_f32_16x16x32_bf16 v[70:73], v[130:133], v[178:181], v[70:73]
	v_mfma_f32_16x16x32_bf16 v[70:73], v[142:145], v[190:193], v[70:73]
	v_mfma_f32_16x16x32_bf16 v[74:77], v[118:121], v[190:193], v[74:77]
	v_mfma_f32_16x16x32_bf16 v[74:77], v[106:109], v[178:181], v[74:77]
	s_setprio 0
	s_barrier
	ds_read_b128 v[150:153], v234 offset:49152
	ds_read_b128 v[154:157], v234 offset:50176
	ds_read_b128 v[158:161], v234 offset:51200
	ds_read_b128 v[162:165], v234 offset:52224
	ds_read_b128 v[170:173], v234 offset:53248
	ds_read_b128 v[174:177], v234 offset:54272
	ds_read_b128 v[178:181], v234 offset:55296
	ds_read_b128 v[190:193], v234 offset:56320
	s_add_i32 s18, s49, s26
	s_add_u32 vcc_lo, s22, s94
	s_addc_u32 vcc_hi, s23, s95
	s_mov_b32 m0, s18
	s_nop 0
	global_load_lds_dwordx4 v194, vcc
	s_add_i32 m0, s18, 0x2000
	s_add_u32 s18, s22, 0x160080
	s_addc_u32 s19, s23, 0
	s_add_i32 s22, s50, s26
	global_load_lds_dwordx4 v204, vcc
	s_mov_b32 m0, s22
	s_nop 0
	global_load_lds_dwordx4 v194, s[18:19]
	s_add_i32 m0, s22, 0x2000
	s_nop 0
	global_load_lds_dwordx4 v204, s[18:19]
	s_waitcnt vmcnt(6)
	s_waitcnt lgkmcnt(0)
	v_mfma_f32_16x16x32_bf16 v[62:65], v[66:69], v[150:153], v[62:65]
	v_mfma_f32_16x16x32_bf16 v[62:65], v[78:81], v[154:157], v[62:65]
	s_barrier
	s_setprio 1
	v_mfma_f32_16x16x32_bf16 v[58:61], v[98:101], v[154:157], v[58:61]
	v_mfma_f32_16x16x32_bf16 v[58:61], v[86:89], v[150:153], v[58:61]
	v_mfma_f32_16x16x32_bf16 v[42:45], v[86:89], v[158:161], v[42:45]
	v_mfma_f32_16x16x32_bf16 v[42:45], v[98:101], v[162:165], v[42:45]
	v_mfma_f32_16x16x32_bf16 v[46:49], v[78:81], v[162:165], v[46:49]
	v_mfma_f32_16x16x32_bf16 v[46:49], v[66:69], v[158:161], v[46:49]
	v_mfma_f32_16x16x32_bf16 v[30:33], v[66:69], v[170:173], v[30:33]
	v_mfma_f32_16x16x32_bf16 v[30:33], v[78:81], v[174:177], v[30:33]
	v_mfma_f32_16x16x32_bf16 v[26:29], v[98:101], v[174:177], v[26:29]
	v_mfma_f32_16x16x32_bf16 v[26:29], v[86:89], v[170:173], v[26:29]
	v_mfma_f32_16x16x32_bf16 v[10:13], v[86:89], v[178:181], v[10:13]
	v_mfma_f32_16x16x32_bf16 v[10:13], v[98:101], v[190:193], v[10:13]
	s_add_i32 s48, s48, 2
	v_mfma_f32_16x16x32_bf16 v[14:17], v[78:81], v[190:193], v[14:17]
	v_mfma_f32_16x16x32_bf16 v[14:17], v[66:69], v[178:181], v[14:17]
	s_add_u32 s46, s46, 0x100
	v_mfma_f32_16x16x32_bf16 v[54:57], v[106:109], v[150:153], v[54:57]
	v_mfma_f32_16x16x32_bf16 v[54:57], v[118:121], v[154:157], v[54:57]
	s_addc_u32 s47, s47, 0
	v_mfma_f32_16x16x32_bf16 v[50:53], v[142:145], v[154:157], v[50:53]
	v_mfma_f32_16x16x32_bf16 v[50:53], v[130:133], v[150:153], v[50:53]
	s_cmpk_gt_u32 s48, 0x55
	v_mfma_f32_16x16x32_bf16 v[34:37], v[130:133], v[158:161], v[34:37]
	v_mfma_f32_16x16x32_bf16 v[34:37], v[142:145], v[162:165], v[34:37]
	s_mov_b64 s[18:19], s[20:21]
	v_mfma_f32_16x16x32_bf16 v[38:41], v[118:121], v[162:165], v[38:41]
	v_mfma_f32_16x16x32_bf16 v[38:41], v[106:109], v[158:161], v[38:41]
	v_mfma_f32_16x16x32_bf16 v[22:25], v[106:109], v[170:173], v[22:25]
	v_mfma_f32_16x16x32_bf16 v[22:25], v[118:121], v[174:177], v[22:25]
	v_mfma_f32_16x16x32_bf16 v[18:21], v[142:145], v[174:177], v[18:21]
	v_mfma_f32_16x16x32_bf16 v[18:21], v[130:133], v[170:173], v[18:21]
	v_mfma_f32_16x16x32_bf16 v[2:5], v[130:133], v[178:181], v[2:5]
	v_mfma_f32_16x16x32_bf16 v[2:5], v[142:145], v[190:193], v[2:5]
	v_mfma_f32_16x16x32_bf16 v[6:9], v[118:121], v[190:193], v[6:9]
	v_mfma_f32_16x16x32_bf16 v[6:9], v[106:109], v[178:181], v[6:9]
	s_setprio 0
	s_barrier
	s_cbranch_scc0 .LBB0_1441

.Lrealign_9:
.LBB0_1511:
	s_add_u32 vcc_lo, s18, 0xffea0000
	s_addc_u32 vcc_hi, s19, -1
	s_mov_b32 m0, s44
	s_nop 0
	global_load_lds_dwordx4 v210, vcc
	s_mov_b32 m0, s45
	s_nop 0
	global_load_lds_dwordx4 v212, vcc
	ds_read_b128 v[162:165], v237
	ds_read_b128 v[166:169], v237 offset:1024
	ds_read_b128 v[170:173], v237 offset:2048
	ds_read_b128 v[174:177], v237 offset:3072
	ds_read_b128 v[178:181], v237 offset:4096
	ds_read_b128 v[182:185], v237 offset:5120
	ds_read_b128 v[186:189], v237 offset:6144
	ds_read_b128 v[190:193], v237 offset:7168
	ds_read_b128 v[130:133], v235
	ds_read_b128 v[134:137], v235 offset:1024
	ds_read_b128 v[138:141], v235 offset:2048
	ds_read_b128 v[142:145], v235 offset:3072
	ds_read_b128 v[146:149], v235 offset:16384
	ds_read_b128 v[150:153], v235 offset:17408
	ds_read_b128 v[154:157], v235 offset:18432
	ds_read_b128 v[158:161], v235 offset:19456
	s_add_i32 s55, s26, 2
	s_add_u32 s24, s18, 0x100
	s_addc_u32 s25, s19, 0
	s_add_i32 s56, 0, 0x10000
	s_cmp_eq_u32 s15, s26
	s_cselect_b32 s29, s7, s25
	s_cselect_b32 s28, s6, s24
	s_cselect_b32 s27, s17, s54
	s_cselect_b32 s26, s16, s23
	s_add_i32 s57, 0, 0x14000
	s_add_i32 m0, s40, 0xc000
	s_nop 0
	global_load_lds_dwordx4 v210, s[18:19]
	s_add_i32 m0, s40, 0xe000
	s_nop 0
	global_load_lds_dwordx4 v212, s[18:19]
	s_waitcnt vmcnt(8)
	s_waitcnt lgkmcnt(0)
	v_mfma_f32_16x16x32_bf16 v[126:129], v[130:133], v[162:165], v[126:129]
	v_mfma_f32_16x16x32_bf16 v[126:129], v[134:137], v[166:169], v[126:129]
	s_barrier
	s_setprio 1
	v_mfma_f32_16x16x32_bf16 v[122:125], v[142:145], v[166:169], v[122:125]
	v_mfma_f32_16x16x32_bf16 v[122:125], v[138:141], v[162:165], v[122:125]
	v_mfma_f32_16x16x32_bf16 v[106:109], v[138:141], v[170:173], v[106:109]
	v_mfma_f32_16x16x32_bf16 v[106:109], v[142:145], v[174:177], v[106:109]
	v_mfma_f32_16x16x32_bf16 v[110:113], v[134:137], v[174:177], v[110:113]
	v_mfma_f32_16x16x32_bf16 v[110:113], v[130:133], v[170:173], v[110:113]
	v_mfma_f32_16x16x32_bf16 v[94:97], v[130:133], v[178:181], v[94:97]
	v_mfma_f32_16x16x32_bf16 v[94:97], v[134:137], v[182:185], v[94:97]
	v_mfma_f32_16x16x32_bf16 v[90:93], v[142:145], v[182:185], v[90:93]
	v_mfma_f32_16x16x32_bf16 v[90:93], v[138:141], v[178:181], v[90:93]
	v_mfma_f32_16x16x32_bf16 v[74:77], v[138:141], v[186:189], v[74:77]
	v_mfma_f32_16x16x32_bf16 v[74:77], v[142:145], v[190:193], v[74:77]
	v_mfma_f32_16x16x32_bf16 v[78:81], v[134:137], v[190:193], v[78:81]
	v_mfma_f32_16x16x32_bf16 v[78:81], v[130:133], v[186:189], v[78:81]
	v_mfma_f32_16x16x32_bf16 v[118:121], v[146:149], v[162:165], v[118:121]
	v_mfma_f32_16x16x32_bf16 v[118:121], v[150:153], v[166:169], v[118:121]
	v_mfma_f32_16x16x32_bf16 v[114:117], v[158:161], v[166:169], v[114:117]
	v_mfma_f32_16x16x32_bf16 v[114:117], v[154:157], v[162:165], v[114:117]
	v_mfma_f32_16x16x32_bf16 v[98:101], v[154:157], v[170:173], v[98:101]
	v_mfma_f32_16x16x32_bf16 v[98:101], v[158:161], v[174:177], v[98:101]
	v_mfma_f32_16x16x32_bf16 v[102:105], v[150:153], v[174:177], v[102:105]
	v_mfma_f32_16x16x32_bf16 v[102:105], v[146:149], v[170:173], v[102:105]
	v_mfma_f32_16x16x32_bf16 v[86:89], v[146:149], v[178:181], v[86:89]
	v_mfma_f32_16x16x32_bf16 v[86:89], v[150:153], v[182:185], v[86:89]
	v_mfma_f32_16x16x32_bf16 v[82:85], v[158:161], v[182:185], v[82:85]
	v_mfma_f32_16x16x32_bf16 v[82:85], v[154:157], v[178:181], v[82:85]
	v_mfma_f32_16x16x32_bf16 v[66:69], v[154:157], v[186:189], v[66:69]
	v_mfma_f32_16x16x32_bf16 v[66:69], v[158:161], v[190:193], v[66:69]
	v_mfma_f32_16x16x32_bf16 v[70:73], v[150:153], v[190:193], v[70:73]
	v_mfma_f32_16x16x32_bf16 v[70:73], v[146:149], v[186:189], v[70:73]
	s_setprio 0
	s_barrier
	ds_read_b128 v[162:165], v237 offset:16384
	ds_read_b128 v[166:169], v237 offset:17408
	ds_read_b128 v[170:173], v237 offset:18432
	ds_read_b128 v[174:177], v237 offset:19456
	ds_read_b128 v[178:181], v237 offset:20480
	ds_read_b128 v[182:185], v237 offset:21504
	ds_read_b128 v[186:189], v237 offset:22528
	ds_read_b128 v[190:193], v237 offset:23552
	s_add_i32 s18, s56, s39
	s_mov_b32 m0, s18
	s_nop 0
	global_load_lds_dwordx4 v194, s[26:27]
	s_add_i32 m0, s18, 0x2000
	s_add_u32 s18, s26, 0x160000
	s_addc_u32 s19, s27, 0
	s_add_i32 s56, s57, s39
	global_load_lds_dwordx4 v208, s[26:27]
	s_mov_b32 m0, s56
	s_nop 0
	global_load_lds_dwordx4 v194, s[18:19]
	s_add_i32 m0, s56, 0x2000
	s_nop 0
	global_load_lds_dwordx4 v208, s[18:19]
	s_waitcnt vmcnt(6)
	s_waitcnt lgkmcnt(0)
	v_mfma_f32_16x16x32_bf16 v[62:65], v[130:133], v[162:165], v[62:65]
	v_mfma_f32_16x16x32_bf16 v[62:65], v[134:137], v[166:169], v[62:65]
	s_barrier
	s_setprio 1
	v_mfma_f32_16x16x32_bf16 v[58:61], v[142:145], v[166:169], v[58:61]
	v_mfma_f32_16x16x32_bf16 v[58:61], v[138:141], v[162:165], v[58:61]
	v_mfma_f32_16x16x32_bf16 v[42:45], v[138:141], v[170:173], v[42:45]
	v_mfma_f32_16x16x32_bf16 v[42:45], v[142:145], v[174:177], v[42:45]
	v_mfma_f32_16x16x32_bf16 v[46:49], v[134:137], v[174:177], v[46:49]
	v_mfma_f32_16x16x32_bf16 v[46:49], v[130:133], v[170:173], v[46:49]
	v_mfma_f32_16x16x32_bf16 v[30:33], v[130:133], v[178:181], v[30:33]
	v_mfma_f32_16x16x32_bf16 v[30:33], v[134:137], v[182:185], v[30:33]
	v_mfma_f32_16x16x32_bf16 v[26:29], v[142:145], v[182:185], v[26:29]
	v_mfma_f32_16x16x32_bf16 v[26:29], v[138:141], v[178:181], v[26:29]
	v_mfma_f32_16x16x32_bf16 v[10:13], v[138:141], v[186:189], v[10:13]
	v_mfma_f32_16x16x32_bf16 v[10:13], v[142:145], v[190:193], v[10:13]
	v_mfma_f32_16x16x32_bf16 v[14:17], v[134:137], v[190:193], v[14:17]
	v_mfma_f32_16x16x32_bf16 v[14:17], v[130:133], v[186:189], v[14:17]
	v_mfma_f32_16x16x32_bf16 v[54:57], v[146:149], v[162:165], v[54:57]
	v_mfma_f32_16x16x32_bf16 v[54:57], v[150:153], v[166:169], v[54:57]
	v_mfma_f32_16x16x32_bf16 v[50:53], v[158:161], v[166:169], v[50:53]
	v_mfma_f32_16x16x32_bf16 v[50:53], v[154:157], v[162:165], v[50:53]
	v_mfma_f32_16x16x32_bf16 v[34:37], v[154:157], v[170:173], v[34:37]
	v_mfma_f32_16x16x32_bf16 v[34:37], v[158:161], v[174:177], v[34:37]
	v_mfma_f32_16x16x32_bf16 v[38:41], v[150:153], v[174:177], v[38:41]
	v_mfma_f32_16x16x32_bf16 v[38:41], v[146:149], v[170:173], v[38:41]
	v_mfma_f32_16x16x32_bf16 v[22:25], v[146:149], v[178:181], v[22:25]
	v_mfma_f32_16x16x32_bf16 v[22:25], v[150:153], v[182:185], v[22:25]
	v_mfma_f32_16x16x32_bf16 v[18:21], v[158:161], v[182:185], v[18:21]
	v_mfma_f32_16x16x32_bf16 v[18:21], v[154:157], v[178:181], v[18:21]
	v_mfma_f32_16x16x32_bf16 v[2:5], v[154:157], v[186:189], v[2:5]
	v_mfma_f32_16x16x32_bf16 v[2:5], v[158:161], v[190:193], v[2:5]
	v_mfma_f32_16x16x32_bf16 v[6:9], v[150:153], v[190:193], v[6:9]
	v_mfma_f32_16x16x32_bf16 v[6:9], v[146:149], v[186:189], v[6:9]
	s_setprio 0
	s_barrier
	s_mov_b32 m0, s40
	s_nop 0
	global_load_lds_dwordx4 v204, s[28:29]
	s_mov_b32 m0, s41
	s_nop 0
	global_load_lds_dwordx4 v206, s[28:29]
	ds_read_b128 v[162:165], v237 offset:32768
	ds_read_b128 v[166:169], v237 offset:33792
	ds_read_b128 v[170:173], v237 offset:34816
	ds_read_b128 v[174:177], v237 offset:35840
	ds_read_b128 v[178:181], v237 offset:36864
	ds_read_b128 v[182:185], v237 offset:37888
	ds_read_b128 v[186:189], v237 offset:38912
	ds_read_b128 v[190:193], v237 offset:39936
	ds_read_b128 v[130:133], v235 offset:32768
	ds_read_b128 v[134:137], v235 offset:33792
	ds_read_b128 v[138:141], v235 offset:34816
	ds_read_b128 v[142:145], v235 offset:35840
	ds_read_b128 v[146:149], v235 offset:49152
	ds_read_b128 v[150:153], v235 offset:50176
	ds_read_b128 v[154:157], v235 offset:51200
	ds_read_b128 v[158:161], v235 offset:52224
	s_add_i32 s56, 0, 0x18000
	s_add_i32 s57, 0, 0x1c000
	s_add_u32 s18, s28, 0x160000
	s_addc_u32 s19, s29, 0
	s_mov_b32 m0, s42
	s_nop 0
	global_load_lds_dwordx4 v204, s[18:19]
	s_mov_b32 m0, s43
	s_nop 0
	global_load_lds_dwordx4 v206, s[18:19]
	s_waitcnt vmcnt(8)
	s_waitcnt lgkmcnt(0)
	v_mfma_f32_16x16x32_bf16 v[126:129], v[130:133], v[162:165], v[126:129]
	v_mfma_f32_16x16x32_bf16 v[126:129], v[134:137], v[166:169], v[126:129]
	s_barrier
	s_setprio 1
	v_mfma_f32_16x16x32_bf16 v[122:125], v[142:145], v[166:169], v[122:125]
	v_mfma_f32_16x16x32_bf16 v[122:125], v[138:141], v[162:165], v[122:125]
	v_mfma_f32_16x16x32_bf16 v[106:109], v[138:141], v[170:173], v[106:109]
	v_mfma_f32_16x16x32_bf16 v[106:109], v[142:145], v[174:177], v[106:109]
	v_mfma_f32_16x16x32_bf16 v[110:113], v[134:137], v[174:177], v[110:113]
	v_mfma_f32_16x16x32_bf16 v[110:113], v[130:133], v[170:173], v[110:113]
	v_mfma_f32_16x16x32_bf16 v[94:97], v[130:133], v[178:181], v[94:97]
	v_mfma_f32_16x16x32_bf16 v[94:97], v[134:137], v[182:185], v[94:97]
	v_mfma_f32_16x16x32_bf16 v[90:93], v[142:145], v[182:185], v[90:93]
	v_mfma_f32_16x16x32_bf16 v[90:93], v[138:141], v[178:181], v[90:93]
	v_mfma_f32_16x16x32_bf16 v[74:77], v[138:141], v[186:189], v[74:77]
	v_mfma_f32_16x16x32_bf16 v[74:77], v[142:145], v[190:193], v[74:77]
	v_mfma_f32_16x16x32_bf16 v[78:81], v[134:137], v[190:193], v[78:81]
	v_mfma_f32_16x16x32_bf16 v[78:81], v[130:133], v[186:189], v[78:81]
	v_mfma_f32_16x16x32_bf16 v[118:121], v[146:149], v[162:165], v[118:121]
	v_mfma_f32_16x16x32_bf16 v[118:121], v[150:153], v[166:169], v[118:121]
	v_mfma_f32_16x16x32_bf16 v[114:117], v[158:161], v[166:169], v[114:117]
	v_mfma_f32_16x16x32_bf16 v[114:117], v[154:157], v[162:165], v[114:117]
	v_mfma_f32_16x16x32_bf16 v[98:101], v[154:157], v[170:173], v[98:101]
	v_mfma_f32_16x16x32_bf16 v[98:101], v[158:161], v[174:177], v[98:101]
	v_mfma_f32_16x16x32_bf16 v[102:105], v[150:153], v[174:177], v[102:105]
	v_mfma_f32_16x16x32_bf16 v[102:105], v[146:149], v[170:173], v[102:105]
	v_mfma_f32_16x16x32_bf16 v[86:89], v[146:149], v[178:181], v[86:89]
	v_mfma_f32_16x16x32_bf16 v[86:89], v[150:153], v[182:185], v[86:89]
	v_mfma_f32_16x16x32_bf16 v[82:85], v[158:161], v[182:185], v[82:85]
	v_mfma_f32_16x16x32_bf16 v[82:85], v[154:157], v[178:181], v[82:85]
	v_mfma_f32_16x16x32_bf16 v[66:69], v[154:157], v[186:189], v[66:69]
	v_mfma_f32_16x16x32_bf16 v[66:69], v[158:161], v[190:193], v[66:69]
	v_mfma_f32_16x16x32_bf16 v[70:73], v[150:153], v[190:193], v[70:73]
	v_mfma_f32_16x16x32_bf16 v[70:73], v[146:149], v[186:189], v[70:73]
	s_setprio 0
	s_barrier
	ds_read_b128 v[162:165], v237 offset:49152
	ds_read_b128 v[166:169], v237 offset:50176
	ds_read_b128 v[170:173], v237 offset:51200
	ds_read_b128 v[174:177], v237 offset:52224
	ds_read_b128 v[178:181], v237 offset:53248
	ds_read_b128 v[182:185], v237 offset:54272
	ds_read_b128 v[186:189], v237 offset:55296
	ds_read_b128 v[190:193], v237 offset:56320
	s_add_i32 s18, s56, s39
	s_add_u32 vcc_lo, s26, s94
	s_addc_u32 vcc_hi, s27, s95
	s_mov_b32 m0, s18
	s_nop 0
	global_load_lds_dwordx4 v194, vcc
	s_add_i32 m0, s18, 0x2000
	s_add_u32 s18, s26, 0x160080
	s_addc_u32 s19, s27, 0
	s_add_i32 s26, s57, s39
	global_load_lds_dwordx4 v208, vcc
	s_mov_b32 m0, s26
	s_nop 0
	global_load_lds_dwordx4 v194, s[18:19]
	s_add_i32 m0, s26, 0x2000
	s_nop 0
	global_load_lds_dwordx4 v208, s[18:19]
	s_waitcnt vmcnt(6)
	s_waitcnt lgkmcnt(0)
	v_mfma_f32_16x16x32_bf16 v[62:65], v[130:133], v[162:165], v[62:65]
	v_mfma_f32_16x16x32_bf16 v[62:65], v[134:137], v[166:169], v[62:65]
	s_barrier
	s_setprio 1
	v_mfma_f32_16x16x32_bf16 v[58:61], v[142:145], v[166:169], v[58:61]
	v_mfma_f32_16x16x32_bf16 v[58:61], v[138:141], v[162:165], v[58:61]
	v_mfma_f32_16x16x32_bf16 v[42:45], v[138:141], v[170:173], v[42:45]
	v_mfma_f32_16x16x32_bf16 v[42:45], v[142:145], v[174:177], v[42:45]
	v_mfma_f32_16x16x32_bf16 v[46:49], v[134:137], v[174:177], v[46:49]
	v_mfma_f32_16x16x32_bf16 v[46:49], v[130:133], v[170:173], v[46:49]
	v_mfma_f32_16x16x32_bf16 v[30:33], v[130:133], v[178:181], v[30:33]
	v_mfma_f32_16x16x32_bf16 v[30:33], v[134:137], v[182:185], v[30:33]
	v_mfma_f32_16x16x32_bf16 v[26:29], v[142:145], v[182:185], v[26:29]
	v_mfma_f32_16x16x32_bf16 v[26:29], v[138:141], v[178:181], v[26:29]
	v_mfma_f32_16x16x32_bf16 v[10:13], v[138:141], v[186:189], v[10:13]
	v_mfma_f32_16x16x32_bf16 v[10:13], v[142:145], v[190:193], v[10:13]
	s_add_u32 s23, s23, 0x100
	v_mfma_f32_16x16x32_bf16 v[14:17], v[134:137], v[190:193], v[14:17]
	v_mfma_f32_16x16x32_bf16 v[14:17], v[130:133], v[186:189], v[14:17]
	s_addc_u32 s54, s54, 0
	v_mfma_f32_16x16x32_bf16 v[54:57], v[146:149], v[162:165], v[54:57]
	v_mfma_f32_16x16x32_bf16 v[54:57], v[150:153], v[166:169], v[54:57]
	s_cmp_ge_i32 s55, s21
	v_mfma_f32_16x16x32_bf16 v[50:53], v[158:161], v[166:169], v[50:53]
	v_mfma_f32_16x16x32_bf16 v[50:53], v[154:157], v[162:165], v[50:53]
	s_mov_b64 s[18:19], s[24:25]
	v_mfma_f32_16x16x32_bf16 v[34:37], v[154:157], v[170:173], v[34:37]
	v_mfma_f32_16x16x32_bf16 v[34:37], v[158:161], v[174:177], v[34:37]
	s_mov_b32 s26, s55
	v_mfma_f32_16x16x32_bf16 v[38:41], v[150:153], v[174:177], v[38:41]
	v_mfma_f32_16x16x32_bf16 v[38:41], v[146:149], v[170:173], v[38:41]
	v_mfma_f32_16x16x32_bf16 v[22:25], v[146:149], v[178:181], v[22:25]
	v_mfma_f32_16x16x32_bf16 v[22:25], v[150:153], v[182:185], v[22:25]
	v_mfma_f32_16x16x32_bf16 v[18:21], v[158:161], v[182:185], v[18:21]
	v_mfma_f32_16x16x32_bf16 v[18:21], v[154:157], v[178:181], v[18:21]
	v_mfma_f32_16x16x32_bf16 v[2:5], v[154:157], v[186:189], v[2:5]
	v_mfma_f32_16x16x32_bf16 v[2:5], v[158:161], v[190:193], v[2:5]
	v_mfma_f32_16x16x32_bf16 v[6:9], v[150:153], v[190:193], v[6:9]
	v_mfma_f32_16x16x32_bf16 v[6:9], v[146:149], v[186:189], v[6:9]
	s_setprio 0
	s_barrier
	s_cbranch_scc0 .LBB0_1511
	s_and_b64 vcc, exec, s[12:13]
	s_cbranch_vccz .LBB0_1514
